# MLA attention loop: K/V loads via SGPR base + lane offset, pointer advance on SALU (removes 30 64-bit VALU adds per 2 tiles); attention fmaxf self-canonicalisation maxes dropped; on top of v34
# speedup vs baseline: 1.0087x; 1.0052x over previous
; __device__ __forceinline__ void finishSM(f32x16& p0, f32x16& p1, float alpha, float& l_reg, bf16x8& pa0, bf16x8& pa1, bf16x8& pa2, bf16x8& pa3) {
; #pragma unroll
;   for (int r = 0; r < 16; ++r) p1[r] = __builtin_amdgcn_exp2f(p1[r]);
;   float ps = 0;
; #pragma unroll
;   for (int r = 0; r < 16; ++r) ps += p0[r];
; #pragma unroll
;   for (int r = 0; r < 16; ++r) ps += p1[r];
;   { auto rr = __builtin_amdgcn_permlane32_swap(__float_as_uint(ps), __float_as_uint(ps), false, false);
;     ps = __uint_as_float(rr[0]) + __uint_as_float(rr[1]); }
;   l_reg = l_reg * alpha + ps;
;     ...
;   PK4(p0, 0, pa0); PK4(p0, 8, pa1); PK4(p1, 0, pa2); PK4(p1, 8, pa3);
;     ...
; }
; template <int DK, int NPARK>
; __device__ __forceinline__ void qkt(f32x16& p0, f32x16& p1, const char* Ks, const bf16x8* qr, const char* qpark, int r32, int hi) {
;   p0 = f32x16{}; p1 = f32x16{};
; #pragma unroll
;   for (int d0 = 0; d0 < DK / 16; ++d0) { const int cb = (d0 * 16 + hi * 8) * 2;
;     bf16x8 b0 = *reinterpret_cast<const bf16x8*>(Ks + kswz<DK>(r32, cb));
;     bf16x8 b1 = *reinterpret_cast<const bf16x8*>(Ks + kswz<DK>(32 + r32, cb));
;     bf16x8 q;
;     if constexpr (NPARK > 0) { if (d0 >= DK / 16 - NPARK) q = *reinterpret_cast<const bf16x8*>(qpark + (d0 - (DK / 16 - NPARK)) * 1024); else q = qr[d0]; } else q = qr[d0];
;     p0 = __builtin_amdgcn_mfma_f32_32x32x16_bf16(b0, q, p0, 0, 0, 0);
;     p1 = __builtin_amdgcn_mfma_f32_32x32x16_bf16(b1, q, p1, 0, 0, 0); }
; }
; __device__ __forceinline__ int v_st(int k, int c) { const int kk = (k & ~0xC) | ((k & 4) << 1) | ((k & 8) >> 1); return ((kk >> 3) * 4 + (c >> 5)) * 512 + ((kk & 7) * 32 + (c & 31)) * 2; }
; __device__ __forceinline__ int v_rd_base(int lane) { return ((lane & 3) << 3) | (((lane >> 2) & 3) << 6) | (((lane >> 4) & 1) << 5) | (((lane >> 5) & 1) << 8); }
; template <int OFF> __device__ __forceinline__ s16x4 tr_read(int vb) {
;   s16x4 r; asm volatile("ds_read_b64_tr_b16 %0, %1 offset:%2" : "=&v"(r) : "v"(vb), "i"(OFF) : "memory"); return r;
; }
; template <int D0> __device__ __forceinline__ void pv_one(f32x16& od, int vb, bf16x8 pa0, bf16x8 pa1, bf16x8 pa2, bf16x8 pa3) {
;   const s16x4 l0 = tr_read<v_rd_off(D0, 0, 0)>(vb), h0 = tr_read<v_rd_off(D0, 0, 1)>(vb), l1 = tr_read<v_rd_off(D0, 1, 0)>(vb), h1 = tr_read<v_rd_off(D0, 1, 1)>(vb);
.LBB0_924:
	ds_read_b128 v[64:67], v161 offset:49152
	ds_read_b128 v[68:71], v161 offset:57344
	ds_read_b128 v[194:197], v170 offset:49152
	ds_read_b128 v[198:201], v170 offset:57344
	v_add_f32_e32 v144, 0, v145
	v_add_f32_e32 v144, v187, v144
	s_waitcnt lgkmcnt(3)
	v_mfma_f32_32x32x16_bf16 v[80:95], v[64:67], v[112:115], 0
	v_add_f32_e32 v144, v146, v144
	v_add_f32_e32 v144, v188, v144
	v_add_f32_e32 v144, v186, v144
	v_add_f32_e32 v144, v189, v144
	v_add_f32_e32 v144, v147, v144
	v_add_f32_e32 v144, v185, v144
	v_add_f32_e32 v144, v157, v144
	s_waitcnt lgkmcnt(2)
	v_mfma_f32_32x32x16_bf16 v[64:79], v[68:71], v[112:115], 0
	v_add_f32_e32 v144, v181, v144
	v_add_f32_e32 v144, v179, v144
	v_add_f32_e32 v144, v182, v144
	v_exp_f32_e32 v142, v142
	v_add_f32_e32 v144, v154, v144
	v_exp_f32_e32 v143, v143
	v_add_f32_e32 v144, v155, v144
	s_waitcnt lgkmcnt(1)
	v_mfma_f32_32x32x16_bf16 v[80:95], v[194:197], v[108:111], v[80:95]
	v_exp_f32_e32 v140, v140
	v_add_f32_e32 v144, v156, v144
	v_exp_f32_e32 v141, v141
	v_add_f32_e32 v144, v180, v144
	v_exp_f32_e32 v136, v136
	v_add_f32_e32 v144, v142, v144
	v_exp_f32_e32 v137, v137
	s_waitcnt lgkmcnt(0)
	v_mfma_f32_32x32x16_bf16 v[64:79], v[198:201], v[108:111], v[64:79]
	ds_read_b128 v[194:197], v169 offset:49152
	ds_read_b128 v[198:201], v169 offset:57344
	v_add_f32_e32 v144, v143, v144
	v_exp_f32_e32 v132, v132
	v_add_f32_e32 v144, v140, v144
	v_exp_f32_e32 v133, v133
	v_add_f32_e32 v144, v141, v144
	v_exp_f32_e32 v130, v130
	s_waitcnt lgkmcnt(1)
	v_mfma_f32_32x32x16_bf16 v[80:95], v[194:197], v[120:123], v[80:95]
	v_add_f32_e32 v144, v136, v144
	v_exp_f32_e32 v131, v131
	v_add_f32_e32 v144, v137, v144
	v_exp_f32_e32 v138, v138
	v_add_f32_e32 v144, v132, v144
	v_exp_f32_e32 v139, v139
	v_add_f32_e32 v144, v133, v144
	s_waitcnt lgkmcnt(0)
	v_mfma_f32_32x32x16_bf16 v[64:79], v[198:201], v[120:123], v[64:79]
	ds_read_b128 v[194:197], v168 offset:49152
	ds_read_b128 v[198:201], v168 offset:57344
	v_exp_f32_e32 v134, v134
	v_add_f32_e32 v144, v130, v144
	v_exp_f32_e32 v135, v135
	v_add_f32_e32 v144, v131, v144
	v_exp_f32_e32 v128, v128
	v_add_f32_e32 v144, v138, v144
	s_waitcnt lgkmcnt(1)
	v_mfma_f32_32x32x16_bf16 v[80:95], v[194:197], v[124:127], v[80:95]
	v_exp_f32_e32 v129, v129
	v_add_f32_e32 v144, v139, v144
	v_add_f32_e32 v144, v134, v144
	v_add_f32_e32 v144, v135, v144
	v_add_f32_e32 v144, v128, v144
	v_add_f32_e32 v175, v129, v144
	v_mov_b32_e32 v176, v175
	s_waitcnt lgkmcnt(0)
	v_mfma_f32_32x32x16_bf16 v[64:79], v[198:201], v[124:127], v[64:79]
	ds_read_b128 v[194:197], v167 offset:49152
	ds_read_b128 v[198:201], v167 offset:57344
	v_permlane32_swap_b32_e32 v175, v176
	s_waitcnt lgkmcnt(1)
	v_mfma_f32_32x32x16_bf16 v[80:95], v[194:197], v[116:119], v[80:95]
	s_waitcnt lgkmcnt(0)
	v_mfma_f32_32x32x16_bf16 v[64:79], v[198:201], v[116:119], v[64:79]
	ds_read_b128 v[194:197], v166 offset:49152
	ds_read_b128 v[198:201], v166 offset:57344
	s_waitcnt lgkmcnt(1)
	v_mfma_f32_32x32x16_bf16 v[80:95], v[194:197], v[104:107], v[80:95]
	s_waitcnt lgkmcnt(0)
	v_mfma_f32_32x32x16_bf16 v[64:79], v[198:201], v[104:107], v[64:79]
	ds_read_b128 v[194:197], v172 offset:49152
	ds_read_b128 v[198:201], v172 offset:57344
	s_waitcnt lgkmcnt(1)
	v_mfma_f32_32x32x16_bf16 v[80:95], v[194:197], v[100:103], v[80:95]
	s_waitcnt lgkmcnt(0)
	v_mfma_f32_32x32x16_bf16 v[64:79], v[198:201], v[100:103], v[64:79]
	ds_read_b128 v[194:197], v171 offset:49152
	ds_read_b128 v[198:201], v171 offset:57344
	v_cvt_pk_bf16_f32 v144, v145, v187
	v_cvt_pk_bf16_f32 v145, v146, v188
	v_cvt_pk_bf16_f32 v146, v186, v189
	v_cvt_pk_bf16_f32 v147, v147, v185
	v_cvt_pk_bf16_f32 v184, v157, v181
	v_cvt_pk_bf16_f32 v185, v179, v182
	s_waitcnt lgkmcnt(1)
	v_mfma_f32_32x32x16_bf16 v[80:95], v[194:197], v[96:99], v[80:95]
	v_permlane32_swap_b32_e32 v144, v146
	v_cvt_pk_bf16_f32 v186, v154, v155
	v_cvt_pk_bf16_f32 v187, v156, v180
	v_cvt_pk_bf16_f32 v180, v142, v143
	v_cvt_pk_bf16_f32 v181, v140, v141
	v_cvt_pk_bf16_f32 v182, v136, v137
	s_waitcnt lgkmcnt(0)
	v_mfma_f32_32x32x16_bf16 v[64:79], v[198:201], v[96:99], v[64:79]
	v_cvt_pk_bf16_f32 v183, v132, v133
	v_cvt_pk_bf16_f32 v188, v130, v131
	v_cvt_pk_bf16_f32 v189, v138, v139
	v_cvt_pk_bf16_f32 v190, v134, v135
	v_cvt_pk_bf16_f32 v191, v128, v129
	v_permlane32_swap_b32_e32 v145, v147
	v_permlane32_swap_b32_e32 v184, v186
	v_permlane32_swap_b32_e32 v185, v187
	v_permlane32_swap_b32_e32 v180, v182
	v_permlane32_swap_b32_e32 v181, v183
	v_permlane32_swap_b32_e32 v188, v190
	v_permlane32_swap_b32_e32 v189, v191
	s_add_u32 s46, s10, s0
	s_addc_u32 s47, s11, 0
	s_add_u32 s48, s10, s67
	s_addc_u32 s49, s11, 0
	global_load_dwordx4 v[128:131], v192, s[46:47]
	global_load_dwordx4 v[132:135], v152, s[46:47]
	global_load_dwordx4 v[136:139], v192, s[48:49]
	global_load_dwordx4 v[140:143], v152, s[48:49]
	ds_read_b64_tr_b16 v[194:195], v160 offset:0
	ds_read_b64_tr_b16 v[196:197], v160 offset:0x800
	ds_read_b64_tr_b16 v[198:199], v160 offset:0x1000
	ds_read_b64_tr_b16 v[200:201], v160 offset:0x1800
	ds_read_b64_tr_b16 v[202:203], v160 offset:0x2000
	ds_read_b64_tr_b16 v[204:205], v160 offset:0x2800
	ds_read_b64_tr_b16 v[206:207], v160 offset:0x3000
	ds_read_b64_tr_b16 v[208:209], v160 offset:0x3800
	s_waitcnt lgkmcnt(0)
	s_nop 0
	v_mfma_f32_32x32x16_bf16 v[0:15], v[144:147], v[194:197], v[0:15]
	ds_read_b64_tr_b16 v[194:195], v160 offset:0x200
	ds_read_b64_tr_b16 v[196:197], v160 offset:0xa00
	v_mfma_f32_32x32x16_bf16 v[0:15], v[184:187], v[198:201], v[0:15]
	ds_read_b64_tr_b16 v[198:199], v160 offset:0x1200
	ds_read_b64_tr_b16 v[200:201], v160 offset:0x1a00
	v_mfma_f32_32x32x16_bf16 v[0:15], v[180:183], v[202:205], v[0:15]
	ds_read_b64_tr_b16 v[202:203], v160 offset:0x2200
	ds_read_b64_tr_b16 v[204:205], v160 offset:0x2a00
	v_mfma_f32_32x32x16_bf16 v[0:15], v[188:191], v[206:209], v[0:15]
	ds_read_b64_tr_b16 v[206:207], v160 offset:0x3200
	ds_read_b64_tr_b16 v[208:209], v160 offset:0x3a00
	s_waitcnt lgkmcnt(0)
; #define SBAR() __builtin_amdgcn_sched_barrier(0)
; template <int DK>
; __device__ __forceinline__ void partialSM(f32x16& p0, f32x16& p1, float& m_reg, float& mn, float& alpha) {
;   constexpr float SCALE = Cst<DK>::SCALE, C = SCALE * 1.4426950408889634f;
;   float pmax = p0[0];
; #pragma unroll
;   for (int r = 1; r < 16; ++r) pmax = fmaxf(pmax, p0[r]);
; #pragma unroll
;   for (int r = 0; r < 16; ++r) pmax = fmaxf(pmax, p1[r]);
;   { auto rr = __builtin_amdgcn_permlane32_swap(__float_as_uint(pmax), __float_as_uint(pmax), false, false);
;     pmax = fmaxf(__uint_as_float(rr[0]), __uint_as_float(rr[1])); }
;   if (__builtin_expect(__all(pmax - m_reg <= THR / SCALE), 1)) { mn = m_reg; alpha = 1.f; }
;   else { mn = fmaxf(m_reg, pmax); alpha = __builtin_amdgcn_exp2f((m_reg - mn) * C); m_reg = mn; }
; template <int D0> __device__ __forceinline__ void pv_one(f32x16& od, int vb, bf16x8 pa0, bf16x8 pa1, bf16x8 pa2, bf16x8 pa3) {
;   const s16x4 l0 = tr_read<v_rd_off(D0, 0, 0)>(vb), h0 = tr_read<v_rd_off(D0, 0, 1)>(vb), l1 = tr_read<v_rd_off(D0, 1, 0)>(vb), h1 = tr_read<v_rd_off(D0, 1, 1)>(vb);
;   const s16x4 l2 = tr_read<v_rd_off(D0, 2, 0)>(vb), h2 = tr_read<v_rd_off(D0, 2, 1)>(vb), l3 = tr_read<v_rd_off(D0, 3, 0)>(vb), h3 = tr_read<v_rd_off(D0, 3, 1)>(vb);
;   asm volatile("s_waitcnt lgkmcnt(0)" ::: "memory"); SBAR();
;     ...
;   od = __builtin_amdgcn_mfma_f32_32x32x16_bf16(pa0, PK(l0, h0), od, 0, 0, 0);
;   od = __builtin_amdgcn_mfma_f32_32x32x16_bf16(pa1, PK(l1, h1), od, 0, 0, 0);
;   od = __builtin_amdgcn_mfma_f32_32x32x16_bf16(pa2, PK(l2, h2), od, 0, 0, 0);
;   od = __builtin_amdgcn_mfma_f32_32x32x16_bf16(pa3, PK(l3, h3), od, 0, 0, 0);
;     ...
; }
; __device__ __forceinline__ void pv_d0(f32x16* o, int vb, bf16x8 pa0, bf16x8 pa1, bf16x8 pa2, bf16x8 pa3) {
;   pv_one<0>(o[0], vb, pa0, pa1, pa2, pa3); pv_one<1>(o[1], vb, pa0, pa1, pa2, pa3); pv_one<2>(o[2], vb, pa0, pa1, pa2, pa3); pv_one<3>(o[3], vb, pa0, pa1, pa2, pa3);
	v_mfma_f32_32x32x16_bf16 v[48:63], v[144:147], v[194:197], v[48:63]
	ds_read_b64_tr_b16 v[194:195], v160 offset:0x400
	ds_read_b64_tr_b16 v[196:197], v160 offset:0xc00
	v_mfma_f32_32x32x16_bf16 v[48:63], v[184:187], v[198:201], v[48:63]
	ds_read_b64_tr_b16 v[198:199], v160 offset:0x1400
	ds_read_b64_tr_b16 v[200:201], v160 offset:0x1c00
	v_mfma_f32_32x32x16_bf16 v[48:63], v[180:183], v[202:205], v[48:63]
	ds_read_b64_tr_b16 v[202:203], v160 offset:0x2400
	ds_read_b64_tr_b16 v[204:205], v160 offset:0x2c00
	v_mfma_f32_32x32x16_bf16 v[48:63], v[188:191], v[206:209], v[48:63]
	ds_read_b64_tr_b16 v[206:207], v160 offset:0x3400
	ds_read_b64_tr_b16 v[208:209], v160 offset:0x3c00
	s_waitcnt lgkmcnt(0)
	v_mfma_f32_32x32x16_bf16 v[32:47], v[144:147], v[194:197], v[32:47]
	ds_read_b64_tr_b16 v[194:195], v160 offset:0x600
	ds_read_b64_tr_b16 v[196:197], v160 offset:0xe00
	v_mfma_f32_32x32x16_bf16 v[32:47], v[184:187], v[198:201], v[32:47]
	ds_read_b64_tr_b16 v[198:199], v160 offset:0x1600
	ds_read_b64_tr_b16 v[200:201], v160 offset:0x1e00
	v_mfma_f32_32x32x16_bf16 v[32:47], v[180:183], v[202:205], v[32:47]
	ds_read_b64_tr_b16 v[202:203], v160 offset:0x2600
	ds_read_b64_tr_b16 v[204:205], v160 offset:0x2e00
	v_mfma_f32_32x32x16_bf16 v[32:47], v[188:191], v[206:209], v[32:47]
	ds_read_b64_tr_b16 v[206:207], v160 offset:0x3600
	ds_read_b64_tr_b16 v[208:209], v160 offset:0x3e00
	s_waitcnt lgkmcnt(0)
	v_mfma_f32_32x32x16_bf16 v[16:31], v[144:147], v[194:197], v[16:31]
	v_max_f32_e32 v144, v80, v81
	v_max3_f32 v144, v144, v82, v83
	v_max3_f32 v144, v144, v84, v85
	v_max3_f32 v144, v144, v86, v87
	v_max3_f32 v144, v144, v88, v89
	v_max3_f32 v144, v144, v90, v91
	v_max3_f32 v144, v144, v92, v93
	v_mfma_f32_32x32x16_bf16 v[16:31], v[184:187], v[198:201], v[16:31]
	v_max3_f32 v144, v144, v94, v95
	v_max3_f32 v144, v144, v64, v65
	v_max3_f32 v144, v144, v66, v67
	v_max3_f32 v144, v144, v68, v69
	v_max3_f32 v144, v144, v70, v71
	v_max3_f32 v144, v144, v72, v73
	v_max3_f32 v144, v144, v74, v75
	v_max3_f32 v144, v144, v76, v77
	v_mfma_f32_32x32x16_bf16 v[16:31], v[180:183], v[202:205], v[16:31]
	v_max3_f32 v144, v144, v78, v79
	v_mov_b32_e32 v145, v144
	s_nop 1
	v_permlane32_swap_b32_e32 v144, v145
	v_max_f32_e32 v144, v144, v145
	v_sub_f32_e32 v145, v144, v174
	v_cmp_ge_f32_e32 vcc, s1, v145
	v_max_f32_e32 v144, v174, v144
	v_mfma_f32_32x32x16_bf16 v[16:31], v[188:191], v[206:209], v[16:31]
	v_sub_f32_e32 v145, v174, v144
	v_mul_f32_e32 v145, 0x3e0293ee, v145
	v_exp_f32_e32 v145, v145
	s_cmp_eq_u64 vcc, exec
	s_cselect_b64 s[8:9], -1, 0
	s_barrier
	s_waitcnt vmcnt(0)
	v_cndmask_b32_e64 v177, v145, 1.0, s[8:9]
	v_cmp_gt_f32_e32 vcc, 1.0, v177
	s_waitcnt vmcnt(3)
	ds_write_b128 v164, v[128:131]
	s_waitcnt vmcnt(2)
	ds_write_b128 v165, v[132:135]
	s_waitcnt vmcnt(1)
	ds_write_b128 v162, v[136:139] offset:32768
	s_waitcnt vmcnt(0)
	ds_write_b128 v163, v[140:143] offset:32768
	s_cbranch_vccz .LBB0_928
	s_and_saveexec_b64 s[12:13], s[6:7]
	ds_write_b32 v151, v177 offset:128
	s_or_b64 exec, exec, s[12:13]
	s_waitcnt lgkmcnt(0)
	v_add_u32_e32 v140, s95, v150
	ds_read_b128 v[128:131], v140 offset:224
	ds_read_b128 v[132:135], v140 offset:192
	ds_read_b128 v[136:139], v140 offset:160
	ds_read_b128 v[140:143], v140 offset:128
	s_waitcnt lgkmcnt(3)
	v_pk_mul_f32 v[12:13], v[12:13], v[128:129]
	s_waitcnt lgkmcnt(2)
	v_pk_mul_f32 v[8:9], v[8:9], v[132:133]
	s_waitcnt lgkmcnt(1)
	v_pk_mul_f32 v[4:5], v[4:5], v[136:137]
	v_pk_mul_f32 v[14:15], v[14:15], v[130:131]
	v_pk_mul_f32 v[10:11], v[10:11], v[134:135]
	v_pk_mul_f32 v[6:7], v[6:7], v[138:139]
	s_waitcnt lgkmcnt(0)
	v_pk_mul_f32 v[2:3], v[2:3], v[142:143]
	v_pk_mul_f32 v[0:1], v[0:1], v[140:141]
	v_pk_mul_f32 v[60:61], v[60:61], v[128:129]
	v_pk_mul_f32 v[56:57], v[56:57], v[132:133]
	v_pk_mul_f32 v[52:53], v[52:53], v[136:137]
	v_pk_mul_f32 v[62:63], v[62:63], v[130:131]
	v_pk_mul_f32 v[58:59], v[58:59], v[134:135]
	v_pk_mul_f32 v[54:55], v[54:55], v[138:139]
	v_pk_mul_f32 v[50:51], v[50:51], v[142:143]
	v_pk_mul_f32 v[48:49], v[48:49], v[140:141]
	v_pk_mul_f32 v[44:45], v[44:45], v[128:129]
	v_pk_mul_f32 v[40:41], v[40:41], v[132:133]
	v_pk_mul_f32 v[36:37], v[36:37], v[136:137]
	v_pk_mul_f32 v[46:47], v[46:47], v[130:131]
	v_pk_mul_f32 v[42:43], v[42:43], v[134:135]
	v_pk_mul_f32 v[38:39], v[38:39], v[138:139]
	v_pk_mul_f32 v[34:35], v[34:35], v[142:143]
	v_pk_mul_f32 v[32:33], v[32:33], v[140:141]
	v_pk_mul_f32 v[28:29], v[28:29], v[128:129]
	v_pk_mul_f32 v[24:25], v[24:25], v[132:133]
	v_pk_mul_f32 v[20:21], v[20:21], v[136:137]
	v_pk_mul_f32 v[30:31], v[30:31], v[130:131]
	v_pk_mul_f32 v[26:27], v[26:27], v[134:135]
	v_pk_mul_f32 v[22:23], v[22:23], v[138:139]
	v_pk_mul_f32 v[18:19], v[18:19], v[142:143]
	v_pk_mul_f32 v[16:17], v[16:17], v[140:141]
; #define SBAR() __builtin_amdgcn_sched_barrier(0)
; template <int DK>
; __device__ __forceinline__ void partialSM(f32x16& p0, f32x16& p1, float& m_reg, float& mn, float& alpha) {
;     ...
;   float mnC = -mn * C;
; #pragma unroll
;   for (int r = 0; r < 16; ++r) p0[r] = fmaf(p0[r], C, mnC);
; #pragma unroll
;   for (int r = 0; r < 16; ++r) p1[r] = fmaf(p1[r], C, mnC);
; #pragma unroll
;   for (int r = 0; r < 16; ++r) p0[r] = __builtin_amdgcn_exp2f(p0[r]);
; }
; __device__ __forceinline__ void finishSM(f32x16& p0, f32x16& p1, float alpha, float& l_reg, bf16x8& pa0, bf16x8& pa1, bf16x8& pa2, bf16x8& pa3) {
; #pragma unroll
;   for (int r = 0; r < 16; ++r) p1[r] = __builtin_amdgcn_exp2f(p1[r]);
; template <int DK, int LDQ, int LDK, int LDV, int LDO, int SDEPTH, int NPARK>
; __device__ __forceinline__ void body(const bf16_t* __restrict__ Qb, const bf16_t* __restrict__ Kh, const bf16_t* __restrict__ Vh, bf16_t* __restrict__ Ob, int seq, char* lds, int tid, int wid) {
;     ...
;     SBAR(); qkt<DK, NPARK>(pA0, pA1, K_lds, qr, qpark, r32, hi);
;     finishSM(pB0, pB1, alB, l_reg, pa0, pa1, pa2, pa3); SBAR();
.LBB0_928:
	v_cndmask_b32_e64 v174, v144, v174, s[8:9]
	v_mul_f32_e32 v144, 0xbe0293ee, v174
	v_fmamk_f32 v80, v80, 0x3e0293ee, v144
	v_fmamk_f32 v81, v81, 0x3e0293ee, v144
	v_fmamk_f32 v82, v82, 0x3e0293ee, v144
	v_fmamk_f32 v83, v83, 0x3e0293ee, v144
	v_fmamk_f32 v84, v84, 0x3e0293ee, v144
	v_fmamk_f32 v85, v85, 0x3e0293ee, v144
	v_fmamk_f32 v86, v86, 0x3e0293ee, v144
	v_fmamk_f32 v87, v87, 0x3e0293ee, v144
	v_fmamk_f32 v88, v88, 0x3e0293ee, v144
	v_fmamk_f32 v89, v89, 0x3e0293ee, v144
	v_fmamk_f32 v90, v90, 0x3e0293ee, v144
	v_fmamk_f32 v91, v91, 0x3e0293ee, v144
	v_fmamk_f32 v92, v92, 0x3e0293ee, v144
	v_fmamk_f32 v93, v93, 0x3e0293ee, v144
	v_fmamk_f32 v94, v94, 0x3e0293ee, v144
	v_fmamk_f32 v95, v95, 0x3e0293ee, v144
	v_fmamk_f32 v184, v64, 0x3e0293ee, v144
	v_fmamk_f32 v185, v65, 0x3e0293ee, v144
	v_fmamk_f32 v186, v66, 0x3e0293ee, v144
	v_fmamk_f32 v187, v67, 0x3e0293ee, v144
	v_fmamk_f32 v188, v68, 0x3e0293ee, v144
	v_fmamk_f32 v146, v69, 0x3e0293ee, v144
	v_fmamk_f32 v147, v70, 0x3e0293ee, v144
	v_fmamk_f32 v179, v71, 0x3e0293ee, v144
	v_fmamk_f32 v180, v72, 0x3e0293ee, v144
	v_fmamk_f32 v181, v73, 0x3e0293ee, v144
	v_fmamk_f32 v182, v74, 0x3e0293ee, v144
	v_fmamk_f32 v183, v75, 0x3e0293ee, v144
	v_fmamk_f32 v145, v76, 0x3e0293ee, v144
	v_fmamk_f32 v189, v77, 0x3e0293ee, v144
	v_fmamk_f32 v190, v78, 0x3e0293ee, v144
	v_fmac_f32_e32 v144, 0x3e0293ee, v79
	v_exp_f32_e32 v141, v80
	v_exp_f32_e32 v143, v81
	v_exp_f32_e32 v139, v82
	v_exp_f32_e32 v142, v83
	v_exp_f32_e32 v138, v84
	v_exp_f32_e32 v140, v85
	v_exp_f32_e32 v136, v86
	v_exp_f32_e32 v137, v87
	v_exp_f32_e32 v133, v88
	v_exp_f32_e32 v135, v89
	v_exp_f32_e32 v132, v90
	v_exp_f32_e32 v134, v91
	v_exp_f32_e32 v129, v92
	v_exp_f32_e32 v131, v93
	v_exp_f32_e32 v128, v94
	v_exp_f32_e32 v130, v95
	s_waitcnt lgkmcnt(0)
	s_barrier
	ds_read_b128 v[64:67], v161 offset:32768
	ds_read_b128 v[68:71], v161 offset:40960
	ds_read_b128 v[194:197], v170 offset:32768
	ds_read_b128 v[198:201], v170 offset:40960
	v_exp_f32_e32 v203, v144
	v_add_f32_e32 v144, 0, v141
	s_waitcnt lgkmcnt(3)
	v_mfma_f32_32x32x16_bf16 v[80:95], v[64:67], v[112:115], 0
	v_add_f32_e32 v144, v143, v144
	v_add_f32_e32 v144, v139, v144
	v_add_f32_e32 v144, v142, v144
	v_add_f32_e32 v144, v138, v144
	v_add_f32_e32 v144, v140, v144
	v_add_f32_e32 v144, v136, v144
	v_add_f32_e32 v144, v137, v144
	s_waitcnt lgkmcnt(2)
	v_mfma_f32_32x32x16_bf16 v[64:79], v[68:71], v[112:115], 0
	v_add_f32_e32 v144, v133, v144
	v_add_f32_e32 v144, v135, v144
	v_add_f32_e32 v144, v132, v144
	v_add_f32_e32 v144, v134, v144
	v_exp_f32_e32 v191, v184
	v_add_f32_e32 v144, v129, v144
	v_exp_f32_e32 v185, v185
	s_waitcnt lgkmcnt(1)
	v_mfma_f32_32x32x16_bf16 v[80:95], v[194:197], v[108:111], v[80:95]
	v_add_f32_e32 v144, v131, v144
	v_add_f32_e32 v144, v128, v144
	v_add_f32_e32 v144, v130, v144
	v_add_f32_e32 v144, v191, v144
	v_add_f32_e32 v144, v185, v144
	v_exp_f32_e32 v179, v179
	v_exp_f32_e32 v180, v180
	s_waitcnt lgkmcnt(0)
	v_mfma_f32_32x32x16_bf16 v[64:79], v[198:201], v[108:111], v[64:79]
	ds_read_b128 v[194:197], v169 offset:32768
	ds_read_b128 v[198:201], v169 offset:40960
	v_exp_f32_e32 v181, v181
	v_exp_f32_e32 v182, v182
	v_exp_f32_e32 v202, v189
	v_exp_f32_e32 v190, v190
	s_waitcnt lgkmcnt(1)
	v_mfma_f32_32x32x16_bf16 v[80:95], v[194:197], v[120:123], v[80:95]
	s_waitcnt lgkmcnt(0)
	v_mfma_f32_32x32x16_bf16 v[64:79], v[198:201], v[120:123], v[64:79]
	ds_read_b128 v[194:197], v168 offset:32768
	ds_read_b128 v[198:201], v168 offset:40960
	s_waitcnt lgkmcnt(1)
	v_mfma_f32_32x32x16_bf16 v[80:95], v[194:197], v[124:127], v[80:95]
	s_waitcnt lgkmcnt(0)
	v_mfma_f32_32x32x16_bf16 v[64:79], v[198:201], v[124:127], v[64:79]
	ds_read_b128 v[194:197], v167 offset:32768
	ds_read_b128 v[198:201], v167 offset:40960
	s_waitcnt lgkmcnt(1)
	v_mfma_f32_32x32x16_bf16 v[80:95], v[194:197], v[116:119], v[80:95]
	s_waitcnt lgkmcnt(0)
	v_mfma_f32_32x32x16_bf16 v[64:79], v[198:201], v[116:119], v[64:79]
	ds_read_b128 v[194:197], v166 offset:32768
	ds_read_b128 v[198:201], v166 offset:40960
	s_waitcnt lgkmcnt(1)
	v_mfma_f32_32x32x16_bf16 v[80:95], v[194:197], v[104:107], v[80:95]
	s_waitcnt lgkmcnt(0)
	v_mfma_f32_32x32x16_bf16 v[64:79], v[198:201], v[104:107], v[64:79]
	ds_read_b128 v[194:197], v172 offset:32768
	ds_read_b128 v[198:201], v172 offset:40960
	s_waitcnt lgkmcnt(1)
	v_mfma_f32_32x32x16_bf16 v[80:95], v[194:197], v[100:103], v[80:95]
	s_waitcnt lgkmcnt(0)
	v_mfma_f32_32x32x16_bf16 v[64:79], v[198:201], v[100:103], v[64:79]
	ds_read_b128 v[194:197], v171 offset:32768
	ds_read_b128 v[198:201], v171 offset:40960
	s_waitcnt lgkmcnt(1)
	v_mfma_f32_32x32x16_bf16 v[80:95], v[194:197], v[96:99], v[80:95]
	v_exp_f32_e32 v195, v186
	v_exp_f32_e32 v196, v187
	v_exp_f32_e32 v197, v188
	v_add_f32_e32 v144, v195, v144
	v_add_f32_e32 v144, v196, v144
	v_add_f32_e32 v144, v197, v144
	s_waitcnt lgkmcnt(0)
; #define SBAR() __builtin_amdgcn_sched_barrier(0)
; __device__ __forceinline__ void finishSM(f32x16& p0, f32x16& p1, float alpha, float& l_reg, bf16x8& pa0, bf16x8& pa1, bf16x8& pa2, bf16x8& pa3) {
; #pragma unroll
;   for (int r = 0; r < 16; ++r) p1[r] = __builtin_amdgcn_exp2f(p1[r]);
;   float ps = 0;
; #pragma unroll
;   for (int r = 0; r < 16; ++r) ps += p0[r];
; #pragma unroll
;   for (int r = 0; r < 16; ++r) ps += p1[r];
;   { auto rr = __builtin_amdgcn_permlane32_swap(__float_as_uint(ps), __float_as_uint(ps), false, false);
;     ps = __uint_as_float(rr[0]) + __uint_as_float(rr[1]); }
;   l_reg = l_reg * alpha + ps;
;     ...
;   PK4(p0, 0, pa0); PK4(p0, 8, pa1); PK4(p1, 0, pa2); PK4(p1, 8, pa3);
;     ...
; }
; template <int D0> __device__ __forceinline__ void pv_one(f32x16& od, int vb, bf16x8 pa0, bf16x8 pa1, bf16x8 pa2, bf16x8 pa3) {
;   const s16x4 l0 = tr_read<v_rd_off(D0, 0, 0)>(vb), h0 = tr_read<v_rd_off(D0, 0, 1)>(vb), l1 = tr_read<v_rd_off(D0, 1, 0)>(vb), h1 = tr_read<v_rd_off(D0, 1, 1)>(vb);
;   const s16x4 l2 = tr_read<v_rd_off(D0, 2, 0)>(vb), h2 = tr_read<v_rd_off(D0, 2, 1)>(vb), l3 = tr_read<v_rd_off(D0, 3, 0)>(vb), h3 = tr_read<v_rd_off(D0, 3, 1)>(vb);
;   asm volatile("s_waitcnt lgkmcnt(0)" ::: "memory"); SBAR();
;     ...
;   od = __builtin_amdgcn_mfma_f32_32x32x16_bf16(pa0, PK(l0, h0), od, 0, 0, 0);
;   od = __builtin_amdgcn_mfma_f32_32x32x16_bf16(pa1, PK(l1, h1), od, 0, 0, 0);
;   od = __builtin_amdgcn_mfma_f32_32x32x16_bf16(pa2, PK(l2, h2), od, 0, 0, 0);
;   od = __builtin_amdgcn_mfma_f32_32x32x16_bf16(pa3, PK(l3, h3), od, 0, 0, 0);
;     ...
; }
; __device__ __forceinline__ void pv_d0(f32x16* o, int vb, bf16x8 pa0, bf16x8 pa1, bf16x8 pa2, bf16x8 pa3) {
;   pv_one<0>(o[0], vb, pa0, pa1, pa2, pa3); pv_one<1>(o[1], vb, pa0, pa1, pa2, pa3); pv_one<2>(o[2], vb, pa0, pa1, pa2, pa3); pv_one<3>(o[3], vb, pa0, pa1, pa2, pa3);
; template <int DK, int LDQ, int LDK, int LDV, int LDO, int SDEPTH, int NPARK>
; __device__ __forceinline__ void body(const bf16_t* __restrict__ Qb, const bf16_t* __restrict__ Kh, const bf16_t* __restrict__ Vh, bf16_t* __restrict__ Ob, int seq, char* lds, int tid, int wid) {
;     ...
;     if (SDEPTH == 1 || j + 3 < NT) SLOAD(SE, (j + 1 + SDEPTH) * KVBLK); SBAR();
;     pv_d0(o, vb0 + (int)SHM_V, pa0, pa1, pa2, pa3); partialSM<DK>(pA0, pA1, m_reg, mnA, alA);
	v_mfma_f32_32x32x16_bf16 v[64:79], v[198:201], v[96:99], v[64:79]
	v_exp_f32_e32 v198, v146
	v_exp_f32_e32 v199, v147
	v_exp_f32_e32 v200, v183
	v_exp_f32_e32 v201, v145
	v_add_f32_e32 v144, v198, v144
	v_add_f32_e32 v144, v199, v144
	v_add_f32_e32 v144, v179, v144
	v_add_f32_e32 v144, v180, v144
	v_add_f32_e32 v144, v181, v144
	v_add_f32_e32 v144, v182, v144
	v_add_f32_e32 v144, v200, v144
	v_add_f32_e32 v144, v201, v144
	v_add_f32_e32 v144, v202, v144
	v_add_f32_e32 v144, v190, v144
	v_add_f32_e32 v183, v203, v144
	v_mov_b32_e32 v184, v183
	v_cvt_pk_bf16_f32 v144, v141, v143
	v_cvt_pk_bf16_f32 v145, v139, v142
	v_cvt_pk_bf16_f32 v146, v138, v140
	v_cvt_pk_bf16_f32 v147, v136, v137
	s_nop 1
	v_permlane32_swap_b32_e32 v183, v184
	v_permlane32_swap_b32_e32 v144, v146
	v_permlane32_swap_b32_e32 v145, v147
	v_cvt_pk_bf16_f32 v186, v133, v135
	v_cvt_pk_bf16_f32 v187, v132, v134
	v_cvt_pk_bf16_f32 v188, v129, v131
	v_cvt_pk_bf16_f32 v189, v128, v130
	v_cvt_pk_bf16_f32 v194, v191, v185
	v_cvt_pk_bf16_f32 v195, v195, v196
	v_cvt_pk_bf16_f32 v196, v197, v198
	v_cvt_pk_bf16_f32 v197, v199, v179
	v_cvt_pk_bf16_f32 v198, v180, v181
	v_cvt_pk_bf16_f32 v199, v182, v200
	v_cvt_pk_bf16_f32 v200, v201, v202
	v_cvt_pk_bf16_f32 v201, v190, v203
	s_nop 0
	v_permlane32_swap_b32_e32 v186, v188
	v_permlane32_swap_b32_e32 v187, v189
	v_permlane32_swap_b32_e32 v194, v196
	v_permlane32_swap_b32_e32 v195, v197
	v_permlane32_swap_b32_e32 v198, v200
	v_permlane32_swap_b32_e32 v199, v201
	s_add_u32 s46, s10, s61
	s_addc_u32 s47, s11, 0
	s_add_u32 s48, s10, s64
	s_addc_u32 s49, s11, 0
	global_load_dwordx4 v[128:131], v192, s[46:47]
	global_load_dwordx4 v[132:135], v152, s[46:47]
	global_load_dwordx4 v[136:139], v192, s[48:49]
	global_load_dwordx4 v[140:143], v152, s[48:49]
	ds_read_b64_tr_b16 v[154:155], v159 offset:0
	ds_read_b64_tr_b16 v[156:157], v159 offset:0x800
	ds_read_b64_tr_b16 v[202:203], v159 offset:0x1000
	ds_read_b64_tr_b16 v[204:205], v159 offset:0x1800
	ds_read_b64_tr_b16 v[206:207], v159 offset:0x2000
	ds_read_b64_tr_b16 v[208:209], v159 offset:0x2800
	ds_read_b64_tr_b16 v[210:211], v159 offset:0x3000
	ds_read_b64_tr_b16 v[212:213], v159 offset:0x3800
	s_waitcnt lgkmcnt(0)
	s_nop 0
	v_mfma_f32_32x32x16_bf16 v[0:15], v[144:147], v[154:157], v[0:15]
	ds_read_b64_tr_b16 v[154:155], v159 offset:0x200
	ds_read_b64_tr_b16 v[156:157], v159 offset:0xa00
	v_mfma_f32_32x32x16_bf16 v[0:15], v[186:189], v[202:205], v[0:15]
	ds_read_b64_tr_b16 v[202:203], v159 offset:0x1200
	ds_read_b64_tr_b16 v[204:205], v159 offset:0x1a00
	v_mfma_f32_32x32x16_bf16 v[0:15], v[194:197], v[206:209], v[0:15]
	ds_read_b64_tr_b16 v[206:207], v159 offset:0x2200
	ds_read_b64_tr_b16 v[208:209], v159 offset:0x2a00
	v_mfma_f32_32x32x16_bf16 v[0:15], v[198:201], v[210:213], v[0:15]
	ds_read_b64_tr_b16 v[210:211], v159 offset:0x3200
	ds_read_b64_tr_b16 v[212:213], v159 offset:0x3a00
	s_waitcnt lgkmcnt(0)
	v_mfma_f32_32x32x16_bf16 v[48:63], v[144:147], v[154:157], v[48:63]
	ds_read_b64_tr_b16 v[154:155], v159 offset:0x400
	ds_read_b64_tr_b16 v[156:157], v159 offset:0xc00
	v_mfma_f32_32x32x16_bf16 v[48:63], v[186:189], v[202:205], v[48:63]
	ds_read_b64_tr_b16 v[202:203], v159 offset:0x1400
	ds_read_b64_tr_b16 v[204:205], v159 offset:0x1c00
	v_mfma_f32_32x32x16_bf16 v[48:63], v[194:197], v[206:209], v[48:63]
	ds_read_b64_tr_b16 v[206:207], v159 offset:0x2400
	ds_read_b64_tr_b16 v[208:209], v159 offset:0x2c00
	v_mfma_f32_32x32x16_bf16 v[48:63], v[198:201], v[210:213], v[48:63]
	ds_read_b64_tr_b16 v[210:211], v159 offset:0x3400
	ds_read_b64_tr_b16 v[212:213], v159 offset:0x3c00
	s_waitcnt lgkmcnt(0)
	v_mfma_f32_32x32x16_bf16 v[32:47], v[144:147], v[154:157], v[32:47]
	ds_read_b64_tr_b16 v[154:155], v159 offset:0x600
	ds_read_b64_tr_b16 v[156:157], v159 offset:0xe00
	v_mfma_f32_32x32x16_bf16 v[32:47], v[186:189], v[202:205], v[32:47]
	ds_read_b64_tr_b16 v[202:203], v159 offset:0x1600
	ds_read_b64_tr_b16 v[204:205], v159 offset:0x1e00
	v_mfma_f32_32x32x16_bf16 v[32:47], v[194:197], v[206:209], v[32:47]
	ds_read_b64_tr_b16 v[206:207], v159 offset:0x2600
	ds_read_b64_tr_b16 v[208:209], v159 offset:0x2e00
	v_mfma_f32_32x32x16_bf16 v[32:47], v[198:201], v[210:213], v[32:47]
	ds_read_b64_tr_b16 v[210:211], v159 offset:0x3600
	ds_read_b64_tr_b16 v[212:213], v159 offset:0x3e00
	s_waitcnt lgkmcnt(0)
	v_mfma_f32_32x32x16_bf16 v[16:31], v[144:147], v[154:157], v[16:31]
	v_max_f32_e32 v144, v80, v81
	v_max3_f32 v144, v144, v82, v83
	v_max3_f32 v144, v144, v84, v85
	v_max3_f32 v144, v144, v86, v87
	v_max3_f32 v144, v144, v88, v89
	v_max3_f32 v144, v144, v90, v91
	v_max3_f32 v144, v144, v92, v93
	v_mfma_f32_32x32x16_bf16 v[16:31], v[186:189], v[202:205], v[16:31]
	v_max3_f32 v144, v144, v94, v95
	v_max3_f32 v144, v144, v64, v65
	v_max3_f32 v144, v144, v66, v67
	v_max3_f32 v144, v144, v68, v69
	v_max3_f32 v144, v144, v70, v71
	v_max3_f32 v144, v144, v72, v73
	v_max3_f32 v144, v144, v74, v75
	v_max3_f32 v144, v144, v76, v77
	v_mfma_f32_32x32x16_bf16 v[16:31], v[194:197], v[206:209], v[16:31]
	v_max3_f32 v144, v144, v78, v79
	v_mov_b32_e32 v145, v144
	s_nop 1
	v_permlane32_swap_b32_e32 v144, v145
	v_max_f32_e32 v144, v144, v145
	v_sub_f32_e32 v145, v144, v174
	v_cmp_ge_f32_e32 vcc, s1, v145
	v_max_f32_e32 v145, v174, v144
	v_mfma_f32_32x32x16_bf16 v[16:31], v[198:201], v[210:213], v[16:31]
	v_sub_f32_e32 v144, v174, v145
	v_mul_f32_e32 v144, 0x3e0293ee, v144
	v_exp_f32_e32 v144, v144
	s_cmp_eq_u64 vcc, exec
	s_cselect_b64 s[8:9], -1, 0
	s_barrier
; #define SWAIT() do { if constexpr (SDEPTH == 2) { if constexpr (DK == 192) asm volatile("s_waitcnt vmcnt(5)" ::: "memory"); else asm volatile("s_waitcnt vmcnt(4)" ::: "memory"); } else asm volatile("s_waitcnt vmcnt(0)" ::: "memory"); } while (0)
; #define RESC(a) do { if (__any((a) < 1.f)) { if (hi == 0) al_l[r32] = (a); asm volatile("s_waitcnt lgkmcnt(0)" ::: "memory"); \
;     _Pragma("unroll") for (int d = 0; d < 4; ++d) _Pragma("unroll") for (int r = 0; r < 16; ++r) o[d][r] *= al_l[crow(r, hi)]; } } while (0)
; template <int DK, int LDQ, int LDK, int LDV, int LDO, int SDEPTH, int NPARK>
; __device__ __forceinline__ void body(const bf16_t* __restrict__ Qb, const bf16_t* __restrict__ Kh, const bf16_t* __restrict__ Vh, bf16_t* __restrict__ Ob, int seq, char* lds, int tid, int wid) {
;     ...
;     __syncthreads(); SWAIT(); SWRITE(1, SO);
;     RESC(alA); __syncthreads();
	s_waitcnt vmcnt(0)
	v_cndmask_b32_e64 v144, v144, 1.0, s[8:9]
	v_cmp_gt_f32_e32 vcc, 1.0, v144
	s_waitcnt vmcnt(3)
	ds_write_b128 v164, v[128:131] offset:16384
	s_waitcnt vmcnt(2)
	ds_write_b128 v165, v[132:135] offset:16384
	s_waitcnt vmcnt(1)
	ds_write_b128 v162, v[136:139] offset:49152
	s_waitcnt vmcnt(0)
	ds_write_b128 v163, v[140:143] offset:49152
	s_cbranch_vccz .LBB0_932
	s_and_saveexec_b64 s[12:13], s[6:7]
	ds_write_b32 v151, v144 offset:128
	s_or_b64 exec, exec, s[12:13]
	s_waitcnt lgkmcnt(0)
	v_add_u32_e32 v140, s95, v150
	ds_read_b128 v[128:131], v140 offset:224
	ds_read_b128 v[132:135], v140 offset:192
	ds_read_b128 v[136:139], v140 offset:160
	ds_read_b128 v[140:143], v140 offset:128
	s_waitcnt lgkmcnt(3)
	v_pk_mul_f32 v[12:13], v[12:13], v[128:129]
	s_waitcnt lgkmcnt(2)
	v_pk_mul_f32 v[8:9], v[8:9], v[132:133]
	s_waitcnt lgkmcnt(1)
	v_pk_mul_f32 v[4:5], v[4:5], v[136:137]
	v_pk_mul_f32 v[14:15], v[14:15], v[130:131]
	v_pk_mul_f32 v[10:11], v[10:11], v[134:135]
	v_pk_mul_f32 v[6:7], v[6:7], v[138:139]
	s_waitcnt lgkmcnt(0)
	v_pk_mul_f32 v[2:3], v[2:3], v[142:143]
	v_pk_mul_f32 v[0:1], v[0:1], v[140:141]
	v_pk_mul_f32 v[60:61], v[60:61], v[128:129]
	v_pk_mul_f32 v[56:57], v[56:57], v[132:133]
	v_pk_mul_f32 v[52:53], v[52:53], v[136:137]
	v_pk_mul_f32 v[62:63], v[62:63], v[130:131]
	v_pk_mul_f32 v[58:59], v[58:59], v[134:135]
	v_pk_mul_f32 v[54:55], v[54:55], v[138:139]
	v_pk_mul_f32 v[50:51], v[50:51], v[142:143]
	v_pk_mul_f32 v[48:49], v[48:49], v[140:141]
	v_pk_mul_f32 v[44:45], v[44:45], v[128:129]
	v_pk_mul_f32 v[40:41], v[40:41], v[132:133]
	v_pk_mul_f32 v[36:37], v[36:37], v[136:137]
	v_pk_mul_f32 v[46:47], v[46:47], v[130:131]
	v_pk_mul_f32 v[42:43], v[42:43], v[134:135]
	v_pk_mul_f32 v[38:39], v[38:39], v[138:139]
	v_pk_mul_f32 v[34:35], v[34:35], v[142:143]
	v_pk_mul_f32 v[32:33], v[32:33], v[140:141]
	v_pk_mul_f32 v[28:29], v[28:29], v[128:129]
	v_pk_mul_f32 v[24:25], v[24:25], v[132:133]
	v_pk_mul_f32 v[20:21], v[20:21], v[136:137]
	v_pk_mul_f32 v[30:31], v[30:31], v[130:131]
	v_pk_mul_f32 v[26:27], v[26:27], v[134:135]
	v_pk_mul_f32 v[22:23], v[22:23], v[138:139]
	v_pk_mul_f32 v[18:19], v[18:19], v[142:143]
	v_pk_mul_f32 v[16:17], v[16:17], v[140:141]

; template <int DK, int LDQ, int LDK, int LDV, int LDO, int SDEPTH, int NPARK>
; __device__ __forceinline__ void body(const bf16_t* __restrict__ Qb, const bf16_t* __restrict__ Kh, const bf16_t* __restrict__ Vh, bf16_t* __restrict__ Ob, int seq, char* lds, int tid, int wid) {
;   constexpr int SHM_K = KVBLK * DK * 2, ND0 = DK / 16;
;   const int lane = tid & 63, r32 = lane & 31, hi = lane >> 5;
;   char* V_lds = lds; char* K_lds = lds + 2 * SHM_V;
;   float* ws = (float*)(lds + 2 * SHM_V + 2 * SHM_K) + wid * 64; float* li_l = ws; float* al_l = ws + 32;
;   float m_reg = -1e30f, l_reg = 0; f32x16 o[4] = {}; bf16x8 qr[ND0 - NPARK];
;   const bf16_t* Qw = Qb + (long)(wid * QBLK + r32) * LDQ + hi * 8;
;   char* qpark = lds + 2 * SHM_V + 2 * SHM_K + 2048 + wid * (NPARK * 1024) + lane * 16;
; #pragma unroll
;   for (int d0 = 0; d0 < ND0; ++d0) { const bf16x8 qv = *reinterpret_cast<const bf16x8*>(Qw + d0 * 16); if constexpr (NPARK > 0) { if (d0 >= ND0 - NPARK) *reinterpret_cast<bf16x8*>(qpark + (d0 - (ND0 - NPARK)) * 1024) = qv; else qr[d0] = qv; } else qr[d0] = qv; }
;   const int sr = tid >> 4, sc = (tid & 15) * 8, vst0 = v_st(sr, sc), vst1 = v_st(32 + sr, sc);
;   const int sr2 = tid >> 3, sc2 = 128 + (tid & 7) * 8;
;   const int vb0 = (int)(uintptr_t)V_lds + v_rd_base(lane);
;   struct { bf16x8 vs0, vs1, ks0, ks1, ks2; } sr_[SDEPTH];
;   const unsigned ov0 = (unsigned)(sr * LDV + sc) * 2u, ov1 = (unsigned)((32 + sr) * LDV + sc) * 2u, ok0 = (unsigned)(sr * LDK + sc) * 2u, ok1 = (unsigned)((32 + sr) * LDK + sc) * 2u, ok2 = (unsigned)(sr2 * LDK + sc2) * 2u;
;     ...
;   f32x16 pA0, pA1, pB0, pB1; float mnA, mnB, alA, alB; bf16x8 pa0, pa1, pa2, pa3; const int NT = seq / KVBLK;
; __device__ __forceinline__ void attn_phase(const AttnArgs& a, bool ctxq, char* lds, const int wv) {
;     ...
;     for (int U = blockIdx.x; U < nB; U += G) {
;         int b, h, seq; long qrow;
;         if (U < 256) { const int x = U & 7, j = U >> 3; b = x >> 1; h = 2 * (x & 1) + (j >> 4); qrow = (long)b * SEQ + (j & 15) * 256; seq = SKV; }
;         else { const int V = U - 256, x = V & 7; b = x >> 1; h = 2 * (x & 1) + (V >> 3); qrow = (long)RL + b * CTXL; seq = CTXL; }
;         att::body<192, 768, 768, 512, LDP, 1, 4>(a.QB + qrow * 768 + h * 192, a.KB + ((long)b * SKV) * 768 + h * 192, a.VB + ((long)b * SKV) * 512 + h * 128, a.Y + qrow * LDP + 1024 + h * 128, seq, lds, opaque(tid), wv);
.LBB0_947:
	s_mul_i32 s6, s22, 0x600
	s_mul_hi_u32 s2, s22, 0x600
	s_add_u32 s12, s5, s6
	s_mul_i32 s6, s10, 0xc0
	s_addc_u32 s2, s16, s2
	s_ashr_i32 s7, s6, 31
	s_lshl_b64 s[8:9], s[6:7], 1
	s_add_u32 s28, s12, s8
	s_addc_u32 s29, s2, s9
	s_mul_i32 s26, s11, 0x660000
	s_add_u32 s2, s17, s26
	s_addc_u32 s7, s18, 0
	s_mul_i32 s40, s11, 0x1100
	s_add_u32 s6, s2, s8
	s_addc_u32 s7, s7, s9
	s_lshl_b64 s[12:13], s[40:41], 10
	s_add_u32 s2, s19, s12
	s_addc_u32 s15, s20, s13
	s_lshl_b32 s10, s10, 7
	s_ashr_i32 s11, s10, 31
	s_lshl_b64 s[10:11], s[10:11], 1
	v_mov_b32_e32 v49, v178
	s_add_u32 s14, s2, s10
	v_readlane_b32 s2, v254, 26
	v_and_b32_e32 v156, 31, v49
	v_bfe_u32 v157, v49, 5, 1
	v_or_b32_e32 v2, s2, v156
	v_mov_b64_e32 v[0:1], s[28:29]
	v_mad_u64_u32 v[0:1], s[28:29], v2, s73, v[0:1]
	v_lshlrev_b32_e32 v192, 4, v157
	v_lshl_add_u64 v[36:37], v[0:1], 0, v[192:193]
	global_load_dwordx4 v[0:3], v[36:37], off offset:256
	global_load_dwordx4 v[4:7], v[36:37], off offset:288
	global_load_dwordx4 v[8:11], v[36:37], off offset:320
	global_load_dwordx4 v[12:15], v[36:37], off offset:352
	v_ashrrev_i32_e32 v38, 4, v49
	v_lshlrev_b32_e32 v39, 3, v49
	s_movk_i32 s2, 0x300
	v_and_b32_e32 v24, 0x78, v39
	v_mul_lo_u32 v25, v38, s2
	v_ashrrev_i32_e32 v42, 3, v49
	v_mov_b32_e32 v32, 0x80
	v_lshlrev_b32_e32 v40, 1, v24
	v_or_b32_e32 v24, v25, v24
	v_and_or_b32 v43, v39, 56, v32
	v_mul_lo_u32 v32, v42, s2
	s_addc_u32 s15, s15, s11
	v_add_u32_e32 v41, 32, v38
	v_lshl_or_b32 v50, v38, 10, v40
	v_lshlrev_b32_e32 v54, 1, v24
	v_or_b32_e32 v32, v43, v32
	v_lshl_or_b32 v48, v41, 10, v40
	global_load_dwordx4 v[16:19], v50, s[14:15]
	global_load_dwordx4 v[20:23], v48, s[14:15]
	v_add_u32_e32 v52, 0xc000, v54
	global_load_dwordx4 v[24:27], v54, s[6:7]
	global_load_dwordx4 v[28:31], v52, s[6:7]
	v_lshlrev_b32_e32 v56, 1, v32
	global_load_dwordx4 v[32:35], v56, s[6:7]
	global_load_dwordx4 v[124:127], v[36:37], off
	global_load_dwordx4 v[116:119], v[36:37], off offset:32
	global_load_dwordx4 v[120:123], v[36:37], off offset:64
	global_load_dwordx4 v[112:115], v[36:37], off offset:96
	global_load_dwordx4 v[108:111], v[36:37], off offset:128
	global_load_dwordx4 v[104:107], v[36:37], off offset:160
	global_load_dwordx4 v[100:103], v[36:37], off offset:192
	global_load_dwordx4 v[96:99], v[36:37], off offset:224
	v_and_b32_e32 v90, 63, v49
	v_lshlrev_b32_e32 v51, 4, v90
	v_readlane_b32 s2, v254, 14
	s_movk_i32 s28, 0x180
	v_and_b32_e32 v44, 0xfffff0, v38
	v_add_u32_e32 v183, s2, v51
	s_movk_i32 s2, 0x70
	v_lshlrev_b32_e32 v45, 1, v38
	v_lshrrev_b32_e32 v46, 1, v38
	v_and_b32_e32 v47, 3, v38
	v_and_or_b32 v44, v45, 8, v44
	v_and_or_b32 v45, v46, 4, v47
	v_and_b32_e32 v46, 0xfffff0, v41
	v_lshlrev_b32_e32 v41, 1, v41
	v_bfe_u32 v39, v39, 5, 2
	v_lshrrev_b32_e32 v44, 1, v44
	v_and_or_b32 v41, v41, 8, v46
	v_or_b32_e32 v44, v44, v39
	v_lshrrev_b32_e32 v41, 1, v41
	v_lshlrev_b32_e32 v45, 6, v45
	v_and_b32_e32 v47, 48, v40
	v_lshlrev_b32_e32 v44, 9, v44
	v_or_b32_e32 v39, v41, v39
	v_or3_b32 v41, v44, v45, v47
	v_lshlrev_b32_e32 v39, 9, v39
	v_or3_b32 v36, v39, v45, v47
	v_add_u32_e32 v184, 0, v41
	v_add_u32_e32 v185, 0, v36
	v_or_b32_e32 v87, 32, v192
	v_or_b32_e32 v88, 64, v192
	v_or_b32_e32 v89, 0x60, v192
	s_cmp_lg_u32 0, -1
	s_cselect_b32 s27, 0, 0
	s_add_u32 s14, s14, 0x10000
	s_addc_u32 s15, s15, 0
	s_add_u32 s6, s6, 0x18000
	s_addc_u32 s7, s7, 0
	v_mov_b32_e32 v55, v193
	v_mov_b32_e32 v53, v193
	v_mov_b32_e32 v57, v193
	s_waitcnt vmcnt(0)
	ds_write_b128 v183, v[0:3]
	ds_write_b128 v183, v[4:7] offset:1024
	ds_write_b128 v183, v[8:11] offset:2048
	ds_write_b128 v183, v[12:15] offset:3072
	v_mul_lo_u32 v0, v38, s28
	v_bitop3_b32 v1, v40, v49, s2 bitop3:0x78
	v_lshlrev_b32_e32 v2, 4, v42
	v_add3_u32 v189, v1, v0, 0
	v_lshlrev_b32_e32 v0, 1, v43
	v_mul_lo_u32 v1, v42, s28
	v_and_b32_e32 v2, 0x70, v2
	v_xad_u32 v0, v0, v2, v1
	v_add_u32_e32 v191, 0, v0
	v_lshlrev_b32_e32 v0, 4, v49
	v_mul_u32_u24_e32 v8, 0x180, v156
	v_and_b32_e32 v86, 0x70, v0
	v_bitop3_b32 v0, v192, v8, v86 bitop3:0xde
	v_add_u32_e32 v196, 0, v0
	s_waitcnt vmcnt(0)
	ds_write_b128 v184, v[16:19]
	ds_write_b128 v185, v[20:23]
	ds_write_b128 v189, v[24:27] offset:32768
	ds_write_b128 v189, v[28:31] offset:45056
	ds_write_b128 v191, v[32:35] offset:32768
	s_waitcnt lgkmcnt(0)
	s_barrier
; #define SWAIT() do { if constexpr (SDEPTH == 2) { if constexpr (DK == 192) asm volatile("s_waitcnt vmcnt(5)" ::: "memory"); else asm volatile("s_waitcnt vmcnt(4)" ::: "memory"); } else asm volatile("s_waitcnt vmcnt(0)" ::: "memory"); } while (0)
; template <int DK, int NPARK>
; __device__ __forceinline__ void qkt(f32x16& p0, f32x16& p1, const char* Ks, const bf16x8* qr, const char* qpark, int r32, int hi) {
;   p0 = f32x16{}; p1 = f32x16{};
; #pragma unroll
;   for (int d0 = 0; d0 < DK / 16; ++d0) { const int cb = (d0 * 16 + hi * 8) * 2;
;     bf16x8 b0 = *reinterpret_cast<const bf16x8*>(Ks + kswz<DK>(r32, cb));
;     bf16x8 b1 = *reinterpret_cast<const bf16x8*>(Ks + kswz<DK>(32 + r32, cb));
;     bf16x8 q;
;     if constexpr (NPARK > 0) { if (d0 >= DK / 16 - NPARK) q = *reinterpret_cast<const bf16x8*>(qpark + (d0 - (DK / 16 - NPARK)) * 1024); else q = qr[d0]; } else q = qr[d0];
;     p0 = __builtin_amdgcn_mfma_f32_32x32x16_bf16(b0, q, p0, 0, 0, 0);
;     p1 = __builtin_amdgcn_mfma_f32_32x32x16_bf16(b1, q, p1, 0, 0, 0); }
; template <int DK, int LDQ, int LDK, int LDV, int LDO, int SDEPTH, int NPARK>
; __device__ __forceinline__ void body(const bf16_t* __restrict__ Qb, const bf16_t* __restrict__ Kh, const bf16_t* __restrict__ Vh, bf16_t* __restrict__ Ob, int seq, char* lds, int tid, int wid) {
;     ...
;   SLOAD(SE, 0); asm volatile("s_waitcnt vmcnt(0)" ::: "memory"); SWRITE(0, SE); __syncthreads();
;   qkt<DK, NPARK>(pA0, pA1, K_lds, qr, qpark, r32, hi); partialSM<DK>(pA0, pA1, m_reg, mnA, alA);
;   SLOAD(SO, KVBLK); if constexpr (SDEPTH == 2) { if (2 < NT) SLOAD(SE, 2 * KVBLK); }
;   SWAIT(); SWRITE(1, SO); __syncthreads();
	ds_read_b128 v[0:3], v196 offset:32768
	ds_read_b128 v[4:7], v196 offset:45056
	s_waitcnt lgkmcnt(1)
	v_mfma_f32_32x32x16_bf16 v[32:47], v[0:3], v[124:127], 0
	v_bitop3_b32 v0, v87, v8, v86 bitop3:0xde
	v_add_u32_e32 v199, 0, v0
	s_movk_i32 s2, 0x80
	v_bitop3_b32 v91, v192, v86, s2 bitop3:0x36
	s_movk_i32 s2, 0xa0
	v_bitop3_b32 v92, v192, v86, s2 bitop3:0x36
	s_movk_i32 s2, 0xc0
	s_waitcnt lgkmcnt(0)
	v_mfma_f32_32x32x16_bf16 v[16:31], v[4:7], v[124:127], 0
	ds_read_b128 v[0:3], v199 offset:32768
	ds_read_b128 v[4:7], v199 offset:45056
	v_bitop3_b32 v93, v192, v86, s2 bitop3:0x36
	s_movk_i32 s2, 0xe0
	v_bitop3_b32 v94, v192, v86, s2 bitop3:0x36
	s_movk_i32 s2, 0x100
	v_bitop3_b32 v95, v192, v86, s2 bitop3:0x36
	v_and_b32_e32 v9, 0xc0, v51
	s_waitcnt lgkmcnt(1)
	v_mfma_f32_32x32x16_bf16 v[32:47], v[0:3], v[116:119], v[32:47]
	v_bitop3_b32 v0, v88, v8, v86 bitop3:0xde
	v_add_u32_e32 v198, 0, v0
	s_movk_i32 s2, 0x120
	v_bitop3_b32 v128, v192, v86, s2 bitop3:0x36
	s_movk_i32 s2, 0x140
	v_bitop3_b32 v130, v192, v86, s2 bitop3:0x36
	s_movk_i32 s2, 0x160
	s_waitcnt lgkmcnt(0)
	v_mfma_f32_32x32x16_bf16 v[16:31], v[4:7], v[116:119], v[16:31]
	ds_read_b128 v[0:3], v198 offset:32768
	ds_read_b128 v[4:7], v198 offset:45056
	v_bitop3_b32 v131, v192, v86, s2 bitop3:0x36
	v_add_u32_e32 v202, 0x3000, v189
	s_mov_b32 s40, s41
	s_mov_b32 s42, s41
	s_mov_b32 s43, s41
	s_mov_b32 s44, s41
	s_waitcnt lgkmcnt(1)
	v_mfma_f32_32x32x16_bf16 v[32:47], v[0:3], v[120:123], v[32:47]
	v_bitop3_b32 v0, v89, v8, v86 bitop3:0xde
	v_add_u32_e32 v197, 0, v0
	v_lshlrev_b32_e32 v8, 3, v90
	v_and_or_b32 v9, v8, 24, v9
	s_mov_b32 s45, s41
	s_mov_b32 s46, s41
	s_mov_b32 s47, s41
	s_waitcnt lgkmcnt(0)
	v_mfma_f32_32x32x16_bf16 v[16:31], v[4:7], v[120:123], v[16:31]
	ds_read_b128 v[0:3], v197 offset:32768
	ds_read_b128 v[4:7], v197 offset:45056
	s_mov_b32 s48, s41
	s_mov_b32 s49, s41
	s_mov_b32 s50, s41
	s_mov_b32 s51, s41
	s_mov_b32 s52, s41
	s_mov_b32 s53, s41
	s_waitcnt lgkmcnt(1)
	v_mfma_f32_32x32x16_bf16 v[32:47], v[0:3], v[112:115], v[32:47]
	v_mad_u32_u24 v0, v156, s28, v91
	v_add_u32_e32 v195, 0, v0
	s_mov_b32 s54, s41
	s_mov_b32 s55, s41
	v_mov_b32_e32 v51, v193
	v_lshl_add_u32 v179, v156, 2, s59
	v_mov_b32_e32 v180, 0
	s_waitcnt lgkmcnt(0)
	v_mfma_f32_32x32x16_bf16 v[16:31], v[4:7], v[112:115], v[16:31]
	ds_read_b128 v[0:3], v195 offset:32768
	ds_read_b128 v[4:7], v195 offset:45056
	s_waitcnt lgkmcnt(1)
	v_mfma_f32_32x32x16_bf16 v[32:47], v[0:3], v[108:111], v[32:47]
	v_mad_u32_u24 v0, v156, s28, v92
	v_add_u32_e32 v194, 0, v0
	s_waitcnt lgkmcnt(0)
	v_mfma_f32_32x32x16_bf16 v[16:31], v[4:7], v[108:111], v[16:31]
	ds_read_b128 v[0:3], v194 offset:32768
	ds_read_b128 v[4:7], v194 offset:45056
	s_waitcnt lgkmcnt(1)
	v_mfma_f32_32x32x16_bf16 v[32:47], v[0:3], v[104:107], v[32:47]
	v_mad_u32_u24 v0, v156, s28, v93
	v_add_u32_e32 v188, 0, v0
	s_waitcnt lgkmcnt(0)
	v_mfma_f32_32x32x16_bf16 v[16:31], v[4:7], v[104:107], v[16:31]
	ds_read_b128 v[0:3], v188 offset:32768
	ds_read_b128 v[4:7], v188 offset:45056
	s_waitcnt lgkmcnt(1)
	v_mfma_f32_32x32x16_bf16 v[32:47], v[0:3], v[100:103], v[32:47]
	v_mad_u32_u24 v0, v156, s28, v94
	v_add_u32_e32 v187, 0, v0
	ds_read_b128 v[0:3], v187 offset:32768
	s_waitcnt lgkmcnt(1)
	v_mfma_f32_32x32x16_bf16 v[16:31], v[4:7], v[100:103], v[16:31]
	ds_read_b128 v[4:7], v187 offset:45056
	s_waitcnt lgkmcnt(1)
	v_mfma_f32_32x32x16_bf16 v[32:47], v[0:3], v[96:99], v[32:47]
	v_lshlrev_b32_e32 v0, 1, v49
	v_and_b32_e32 v10, 32, v0
	v_mad_u32_u24 v0, v156, s28, v95
	v_add_u32_e32 v186, 0, v0
	ds_read_b128 v[0:3], v186 offset:32768
	v_mov_b32_e32 v49, v193
	s_waitcnt lgkmcnt(1)
	v_mfma_f32_32x32x16_bf16 v[16:31], v[4:7], v[96:99], v[16:31]
	v_and_b32_e32 v4, 0x100, v8
	v_or3_b32 v148, v9, v10, v4
	ds_read_b128 v[4:7], v183
	ds_read_b128 v[8:11], v186 offset:45056
	ds_read_b128 v[12:15], v183 offset:1024
	v_add_u32_e32 v182, s27, v148
	s_waitcnt lgkmcnt(2)
	v_mfma_f32_32x32x16_bf16 v[32:47], v[0:3], v[4:7], v[32:47]
	v_mad_u32_u24 v0, v156, s28, v128
	v_add_u32_e32 v190, 0, v0
	ds_read_b128 v[0:3], v190 offset:32768
	global_load_dwordx4 v[58:61], v50, s[14:15]
	global_load_dwordx4 v[62:65], v48, s[14:15]
	global_load_dwordx4 v[66:69], v54, s[6:7]
	global_load_dwordx4 v[70:73], v52, s[6:7]
	global_load_dwordx4 v[74:77], v56, s[6:7]
	v_cmp_gt_u32_e64 s[6:7], 32, v90
	s_mov_b32 s14, 2
	s_waitcnt lgkmcnt(2)
	v_mfma_f32_32x32x16_bf16 v[16:31], v[8:11], v[4:7], v[16:31]
	v_mov_b32_e32 v4, 0x3000
	v_mad_u32_u24 v129, v156, s28, v4
	ds_read_b128 v[4:7], v190 offset:45056
	v_bitop3_b32 v173, v192, v129, v86 bitop3:0xde
	v_bitop3_b32 v174, v87, v129, v86 bitop3:0xde
	v_bitop3_b32 v175, v88, v129, v86 bitop3:0xde
	v_bitop3_b32 v176, v89, v129, v86 bitop3:0xde
	s_waitcnt lgkmcnt(1)
	v_mfma_f32_32x32x16_bf16 v[32:47], v[0:3], v[12:15], v[32:47]
	v_mad_u32_u24 v0, v156, s28, v130
	v_add_u32_e32 v201, 0, v0
	ds_read_b128 v[0:3], v201 offset:32768
	v_add_u32_e32 v91, v91, v129
	v_add_u32_e32 v216, 0, v173
	v_add_u32_e32 v214, 0, v174
	v_add_u32_e32 v213, 0, v175
	s_waitcnt lgkmcnt(1)
	v_mfma_f32_32x32x16_bf16 v[16:31], v[4:7], v[12:15], v[16:31]
	ds_read_b128 v[4:7], v183 offset:2048
	ds_read_b128 v[8:11], v201 offset:45056
	ds_read_b128 v[78:81], v183 offset:3072
	v_add_u32_e32 v212, 0, v176
	v_add_u32_e32 v211, 0, v91
	s_waitcnt lgkmcnt(2)
	v_mfma_f32_32x32x16_bf16 v[32:47], v[0:3], v[4:7], v[32:47]
	v_mad_u32_u24 v0, v156, s28, v131
	v_add_u32_e32 v200, 0, v0
	ds_read_b128 v[82:85], v200 offset:32768
	ds_read_b128 v[86:89], v200 offset:45056
	s_waitcnt vmcnt(0)
	s_waitcnt vmcnt(4)
	ds_write_b128 v184, v[58:61] offset:16384
	s_waitcnt vmcnt(3)
; #define SWAIT() do { if constexpr (SDEPTH == 2) { if constexpr (DK == 192) asm volatile("s_waitcnt vmcnt(5)" ::: "memory"); else asm volatile("s_waitcnt vmcnt(4)" ::: "memory"); } else asm volatile("s_waitcnt vmcnt(0)" ::: "memory"); } while (0)
; template <int DK>
; __device__ __forceinline__ void partialSM(f32x16& p0, f32x16& p1, float& m_reg, float& mn, float& alpha) {
;   constexpr float SCALE = Cst<DK>::SCALE, C = SCALE * 1.4426950408889634f;
;   float pmax = p0[0];
; #pragma unroll
;   for (int r = 1; r < 16; ++r) pmax = fmaxf(pmax, p0[r]);
; #pragma unroll
;   for (int r = 0; r < 16; ++r) pmax = fmaxf(pmax, p1[r]);
;   { auto rr = __builtin_amdgcn_permlane32_swap(__float_as_uint(pmax), __float_as_uint(pmax), false, false);
;     pmax = fmaxf(__uint_as_float(rr[0]), __uint_as_float(rr[1])); }
;   if (__builtin_expect(__all(pmax - m_reg <= THR / SCALE), 1)) { mn = m_reg; alpha = 1.f; }
;   else { mn = fmaxf(m_reg, pmax); alpha = __builtin_amdgcn_exp2f((m_reg - mn) * C); m_reg = mn; }
;   float mnC = -mn * C;
; #pragma unroll
;   for (int r = 0; r < 16; ++r) p0[r] = fmaf(p0[r], C, mnC);
; #pragma unroll
;   for (int r = 0; r < 16; ++r) p1[r] = fmaf(p1[r], C, mnC);
; #pragma unroll
;   for (int r = 0; r < 16; ++r) p0[r] = __builtin_amdgcn_exp2f(p0[r]);
; template <int DK, int LDQ, int LDK, int LDV, int LDO, int SDEPTH, int NPARK>
; __device__ __forceinline__ void body(const bf16_t* __restrict__ Qb, const bf16_t* __restrict__ Kh, const bf16_t* __restrict__ Vh, bf16_t* __restrict__ Ob, int seq, char* lds, int tid, int wid) {
;     ...
;   qkt<DK, NPARK>(pA0, pA1, K_lds, qr, qpark, r32, hi); partialSM<DK>(pA0, pA1, m_reg, mnA, alA);
;   SLOAD(SO, KVBLK); if constexpr (SDEPTH == 2) { if (2 < NT) SLOAD(SE, 2 * KVBLK); }
;   SWAIT(); SWRITE(1, SO); __syncthreads();
	ds_write_b128 v185, v[62:65] offset:16384
	s_waitcnt vmcnt(2)
	ds_write_b128 v189, v[66:69] offset:57344
	s_waitcnt vmcnt(1)
	ds_write_b128 v202, v[70:73] offset:57344
	s_waitcnt vmcnt(0)
	ds_write_b128 v191, v[74:77] offset:57344
	s_waitcnt lgkmcnt(8)
	v_mfma_f32_32x32x16_bf16 v[16:31], v[8:11], v[4:7], v[16:31]
	v_mov_b32_e32 v58, 0xf149f2ca
	v_mov_b64_e32 v[0:1], s[40:41]
	v_mov_b64_e32 v[14:15], s[54:55]
	v_mov_b64_e32 v[2:3], s[42:43]
	v_mov_b64_e32 v[4:5], s[44:45]
	v_mov_b64_e32 v[6:7], s[46:47]
	v_mov_b64_e32 v[8:9], s[48:49]
	s_waitcnt lgkmcnt(6)
	v_mfma_f32_32x32x16_bf16 v[32:47], v[82:85], v[78:81], v[32:47]
	v_mov_b64_e32 v[10:11], s[50:51]
	v_mov_b64_e32 v[12:13], s[52:53]
	v_add_u32_e32 v82, v92, v129
	v_add_u32_e32 v83, v93, v129
	v_add_u32_e32 v84, v94, v129
	v_add_u32_e32 v85, v95, v129
	v_add_u32_e32 v92, v128, v129
	s_waitcnt lgkmcnt(5)
	v_mfma_f32_32x32x16_bf16 v[16:31], v[86:89], v[78:81], v[16:31]
	s_nop 2
	v_max_f32_e32 v78, v33, v33
	v_max_f32_e32 v79, v32, v32
	v_max_f32_e32 v78, v79, v78
	v_max3_f32 v78, v78, v34, v35
	v_max3_f32 v78, v78, v36, v37
	v_max3_f32 v78, v78, v38, v39
	v_max3_f32 v78, v78, v40, v41
	v_max3_f32 v78, v78, v42, v43
	v_max3_f32 v78, v78, v44, v45
	v_max3_f32 v78, v78, v46, v47
	v_max3_f32 v78, v78, v16, v17
	v_max3_f32 v78, v78, v18, v19
	v_max3_f32 v78, v78, v20, v21
	v_max3_f32 v78, v78, v22, v23
	v_max3_f32 v78, v78, v24, v25
	v_max3_f32 v78, v78, v26, v27
	v_max3_f32 v78, v78, v28, v29
	v_max3_f32 v78, v78, v30, v31
	v_mov_b32_e32 v79, v78
	s_nop 1
	v_permlane32_swap_b32_e32 v78, v79
	v_max_f32_e32 v79, v79, v79
	v_max_f32_e32 v78, v78, v78
	v_max_f32_e32 v78, v78, v79
	v_add_f32_e32 v79, 0x7149f2ca, v78
	v_cmp_ge_f32_e32 vcc, s69, v79
	s_cmp_eq_u64 vcc, exec
	v_max_f32_e32 v59, 0xf149f2ca, v78
	s_cselect_b64 vcc, -1, 0
	v_cndmask_b32_e32 v210, v59, v58, vcc
	v_mul_f32_e32 v58, 0xbdd53b94, v210
	v_fmamk_f32 v32, v32, 0x3dd53b94, v58
	v_exp_f32_e32 v149, v32
	v_fmamk_f32 v32, v33, 0x3dd53b94, v58
	v_exp_f32_e32 v170, v32
	v_fmamk_f32 v32, v34, 0x3dd53b94, v58
	v_exp_f32_e32 v150, v32
	v_fmamk_f32 v32, v35, 0x3dd53b94, v58
	v_exp_f32_e32 v171, v32
	v_fmamk_f32 v32, v36, 0x3dd53b94, v58
	v_exp_f32_e32 v169, v32
	v_fmamk_f32 v32, v37, 0x3dd53b94, v58
	v_exp_f32_e32 v172, v32
	v_fmamk_f32 v32, v38, 0x3dd53b94, v58
	v_exp_f32_e32 v151, v32
	v_fmamk_f32 v32, v39, 0x3dd53b94, v58
	v_exp_f32_e32 v168, v32
	v_fmamk_f32 v32, v40, 0x3dd53b94, v58
	v_exp_f32_e32 v147, v32
	v_fmamk_f32 v32, v41, 0x3dd53b94, v58
	v_exp_f32_e32 v152, v32
	v_fmamk_f32 v32, v42, 0x3dd53b94, v58
	v_exp_f32_e32 v153, v32
	v_fmamk_f32 v32, v43, 0x3dd53b94, v58
	v_exp_f32_e32 v154, v32
	v_fmamk_f32 v32, v44, 0x3dd53b94, v58
	v_sub_f32_e32 v33, 0xf149f2ca, v59
	v_exp_f32_e32 v144, v32
	v_fmamk_f32 v32, v45, 0x3dd53b94, v58
	v_mul_f32_e32 v33, 0x3dd53b94, v33
	s_addk_i32 s27, 0x4000
	v_exp_f32_e32 v145, v32
	v_fmamk_f32 v32, v46, 0x3dd53b94, v58
	v_exp_f32_e32 v33, v33
	s_add_u32 s8, s26, s8
	v_exp_f32_e32 v146, v32
	v_fmamk_f32 v32, v47, 0x3dd53b94, v58
	s_addc_u32 s9, 0, s9
	v_exp_f32_e32 v155, v32
	s_add_u32 s56, s8, s24
	s_addc_u32 s57, s9, s25
	v_mov_b32_e32 v248, v54
	v_mov_b32_e32 v249, v52
	v_mov_b32_e32 v250, v56
	s_add_u32 s8, s12, s10
	s_addc_u32 s9, s13, s11
	s_add_u32 s32, s8, s24
	s_addc_u32 s33, s9, s25
	v_add_u32_e32 v93, v130, v129
	v_add_u32_e32 v94, v131, v129
	v_cndmask_b32_e64 v215, v33, 1.0, vcc
	v_pk_fma_f32 v[128:129], v[30:31], s[78:79], v[58:59] op_sel_hi:[1,0,0]
	v_pk_fma_f32 v[134:135], v[28:29], s[78:79], v[58:59] op_sel_hi:[1,0,0]
	v_pk_fma_f32 v[138:139], v[26:27], s[78:79], v[58:59] op_sel_hi:[1,0,0]
	v_pk_fma_f32 v[130:131], v[24:25], s[78:79], v[58:59] op_sel_hi:[1,0,0]
	v_pk_fma_f32 v[132:133], v[22:23], s[78:79], v[58:59] op_sel_hi:[1,0,0]
	v_pk_fma_f32 v[136:137], v[20:21], s[78:79], v[58:59] op_sel_hi:[1,0,0]
	v_pk_fma_f32 v[140:141], v[18:19], s[78:79], v[58:59] op_sel_hi:[1,0,0]
	v_pk_fma_f32 v[142:143], v[16:17], s[78:79], v[58:59] op_sel_hi:[1,0,0]
	v_mov_b32_e32 v251, v50
	v_mov_b32_e32 v252, v48
	v_mov_b64_e32 v[62:63], v[14:15]
	v_mov_b64_e32 v[46:47], v[14:15]
	v_mov_b64_e32 v[30:31], v[14:15]
	v_add_u32_e32 v181, s27, v148
	v_add_u32_e32 v209, 0, v82
	v_add_u32_e32 v208, 0, v83
	v_add_u32_e32 v207, 0, v84
	v_add_u32_e32 v206, 0, v85
	v_add_u32_e32 v205, 0, v92
	v_add_u32_e32 v204, 0, v93
	v_add_u32_e32 v203, 0, v94
	v_mov_b64_e32 v[60:61], v[12:13]
	v_mov_b64_e32 v[58:59], v[10:11]
	v_mov_b64_e32 v[56:57], v[8:9]
	v_mov_b64_e32 v[54:55], v[6:7]
	v_mov_b64_e32 v[52:53], v[4:5]
	v_mov_b64_e32 v[50:51], v[2:3]
	v_mov_b64_e32 v[48:49], v[0:1]
	v_mov_b64_e32 v[44:45], v[12:13]
	v_mov_b64_e32 v[42:43], v[10:11]
	v_mov_b64_e32 v[40:41], v[8:9]
	v_mov_b64_e32 v[38:39], v[6:7]
	v_mov_b64_e32 v[36:37], v[4:5]
	v_mov_b64_e32 v[34:35], v[2:3]
	v_mov_b64_e32 v[32:33], v[0:1]
	v_mov_b64_e32 v[28:29], v[12:13]
	v_mov_b64_e32 v[26:27], v[10:11]
	v_mov_b64_e32 v[24:25], v[8:9]
	v_mov_b64_e32 v[22:23], v[6:7]
	v_mov_b64_e32 v[20:21], v[4:5]
	v_mov_b64_e32 v[18:19], v[2:3]
	v_mov_b64_e32 v[16:17], v[0:1]
	s_waitcnt lgkmcnt(0)
	s_barrier
; #define SBAR() __builtin_amdgcn_sched_barrier(0)
; template <int DK, int NPARK>
; __device__ __forceinline__ void qkt(f32x16& p0, f32x16& p1, const char* Ks, const bf16x8* qr, const char* qpark, int r32, int hi) {
;   p0 = f32x16{}; p1 = f32x16{};
; #pragma unroll
;   for (int d0 = 0; d0 < DK / 16; ++d0) { const int cb = (d0 * 16 + hi * 8) * 2;
;     bf16x8 b0 = *reinterpret_cast<const bf16x8*>(Ks + kswz<DK>(r32, cb));
;     bf16x8 b1 = *reinterpret_cast<const bf16x8*>(Ks + kswz<DK>(32 + r32, cb));
;     bf16x8 q;
;     if constexpr (NPARK > 0) { if (d0 >= DK / 16 - NPARK) q = *reinterpret_cast<const bf16x8*>(qpark + (d0 - (DK / 16 - NPARK)) * 1024); else q = qr[d0]; } else q = qr[d0];
;     p0 = __builtin_amdgcn_mfma_f32_32x32x16_bf16(b0, q, p0, 0, 0, 0);
;     p1 = __builtin_amdgcn_mfma_f32_32x32x16_bf16(b1, q, p1, 0, 0, 0); }
; template <int DK, int LDQ, int LDK, int LDV, int LDO, int SDEPTH, int NPARK>
; __device__ __forceinline__ void body(const bf16_t* __restrict__ Qb, const bf16_t* __restrict__ Kh, const bf16_t* __restrict__ Vh, bf16_t* __restrict__ Ob, int seq, char* lds, int tid, int wid) {
;     ...
;     SBAR(); qkt<DK, NPARK>(pB0, pB1, K_lds + SHM_K, qr, qpark, r32, hi);
;     finishSM(pA0, pA1, alA, l_reg, pa0, pa1, pa2, pa3); SBAR();
;     SLOAD(SO, (j + SDEPTH) * KVBLK); SBAR();
;     pv_d0(o, vb0, pa0, pa1, pa2, pa3); partialSM<DK>(pB0, pB1, m_reg, mnB, alB);
.LBB0_948:
	ds_read_b128 v[64:67], v196 offset:57344
	ds_read_b128 v[68:71], v216 offset:57344
	ds_read_b128 v[174:177], v199 offset:57344
	ds_read_b128 v[218:221], v214 offset:57344
	v_add_f32_e32 v148, 0, v149
	v_add_f32_e32 v148, v170, v148
	s_waitcnt lgkmcnt(3)
	v_mfma_f32_32x32x16_bf16 v[80:95], v[64:67], v[124:127], 0
	v_add_f32_e32 v148, v150, v148
	v_add_f32_e32 v148, v171, v148
	v_add_f32_e32 v148, v169, v148
	v_add_f32_e32 v148, v172, v148
	v_add_f32_e32 v148, v151, v148
	v_add_f32_e32 v148, v168, v148
	v_add_f32_e32 v148, v147, v148
	s_waitcnt lgkmcnt(2)
	v_mfma_f32_32x32x16_bf16 v[64:79], v[68:71], v[124:127], 0
	v_add_f32_e32 v148, v152, v148
	v_add_f32_e32 v148, v153, v148
	v_add_f32_e32 v148, v154, v148
	v_exp_f32_e32 v142, v142
	v_add_f32_e32 v148, v144, v148
	v_exp_f32_e32 v143, v143
	v_add_f32_e32 v148, v145, v148
	s_waitcnt lgkmcnt(1)
	v_mfma_f32_32x32x16_bf16 v[80:95], v[174:177], v[116:119], v[80:95]
	v_exp_f32_e32 v140, v140
	v_add_f32_e32 v148, v146, v148
	v_exp_f32_e32 v141, v141
	v_add_f32_e32 v148, v155, v148
	v_exp_f32_e32 v136, v136
	v_add_f32_e32 v148, v142, v148
	v_exp_f32_e32 v137, v137
	s_waitcnt lgkmcnt(0)
	v_mfma_f32_32x32x16_bf16 v[64:79], v[218:221], v[116:119], v[64:79]
	ds_read_b128 v[174:177], v198 offset:57344
	ds_read_b128 v[218:221], v213 offset:57344
	v_add_f32_e32 v148, v143, v148
	v_exp_f32_e32 v132, v132
	v_add_f32_e32 v148, v140, v148
	v_exp_f32_e32 v133, v133
	v_add_f32_e32 v148, v141, v148
	v_exp_f32_e32 v130, v130
	s_waitcnt lgkmcnt(1)
	v_mfma_f32_32x32x16_bf16 v[80:95], v[174:177], v[120:123], v[80:95]
	v_add_f32_e32 v148, v136, v148
	v_exp_f32_e32 v131, v131
	v_add_f32_e32 v148, v137, v148
	v_exp_f32_e32 v138, v138
	v_add_f32_e32 v148, v132, v148
	v_exp_f32_e32 v139, v139
	v_add_f32_e32 v148, v133, v148
	s_waitcnt lgkmcnt(0)
	v_mfma_f32_32x32x16_bf16 v[64:79], v[218:221], v[120:123], v[64:79]
	ds_read_b128 v[174:177], v197 offset:57344
	ds_read_b128 v[218:221], v212 offset:57344
	v_exp_f32_e32 v134, v134
	v_add_f32_e32 v148, v130, v148
	v_exp_f32_e32 v135, v135
	v_add_f32_e32 v148, v131, v148
	v_exp_f32_e32 v128, v128
	v_add_f32_e32 v148, v138, v148
	s_waitcnt lgkmcnt(1)
	v_mfma_f32_32x32x16_bf16 v[80:95], v[174:177], v[112:115], v[80:95]
	v_exp_f32_e32 v129, v129
	v_add_f32_e32 v148, v139, v148
	v_add_f32_e32 v148, v134, v148
	v_add_f32_e32 v148, v135, v148
	v_add_f32_e32 v148, v128, v148
	v_add_f32_e32 v217, v129, v148
	s_waitcnt lgkmcnt(0)
	v_mfma_f32_32x32x16_bf16 v[64:79], v[218:221], v[112:115], v[64:79]
	ds_read_b128 v[174:177], v195 offset:57344
	ds_read_b128 v[218:221], v211 offset:57344
	s_waitcnt lgkmcnt(1)
	v_mfma_f32_32x32x16_bf16 v[80:95], v[174:177], v[108:111], v[80:95]
	s_waitcnt lgkmcnt(0)
	v_mfma_f32_32x32x16_bf16 v[64:79], v[218:221], v[108:111], v[64:79]
	ds_read_b128 v[174:177], v194 offset:57344
	ds_read_b128 v[218:221], v209 offset:57344
	s_waitcnt lgkmcnt(1)
	v_mfma_f32_32x32x16_bf16 v[80:95], v[174:177], v[104:107], v[80:95]
	s_waitcnt lgkmcnt(0)
	v_mfma_f32_32x32x16_bf16 v[64:79], v[218:221], v[104:107], v[64:79]
	ds_read_b128 v[174:177], v188 offset:57344
	ds_read_b128 v[218:221], v208 offset:57344
	s_waitcnt lgkmcnt(1)
	v_mfma_f32_32x32x16_bf16 v[80:95], v[174:177], v[100:103], v[80:95]
	s_waitcnt lgkmcnt(0)
	v_mfma_f32_32x32x16_bf16 v[64:79], v[218:221], v[100:103], v[64:79]
	ds_read_b128 v[174:177], v187 offset:57344
	ds_read_b128 v[218:221], v207 offset:57344
	s_waitcnt lgkmcnt(1)
	v_mfma_f32_32x32x16_bf16 v[80:95], v[174:177], v[96:99], v[80:95]
	s_waitcnt lgkmcnt(0)
	v_mfma_f32_32x32x16_bf16 v[64:79], v[218:221], v[96:99], v[64:79]
	ds_read_b128 v[174:177], v186 offset:57344
	ds_read_b128 v[218:221], v206 offset:57344
	ds_read_b128 v[222:225], v183
	s_waitcnt lgkmcnt(0)
	v_mfma_f32_32x32x16_bf16 v[80:95], v[174:177], v[222:225], v[80:95]
	v_mfma_f32_32x32x16_bf16 v[64:79], v[218:221], v[222:225], v[64:79]
	ds_read_b128 v[174:177], v190 offset:57344
	ds_read_b128 v[218:221], v205 offset:57344
	ds_read_b128 v[222:225], v183 offset:1024
	s_waitcnt lgkmcnt(0)
	v_mfma_f32_32x32x16_bf16 v[80:95], v[174:177], v[222:225], v[80:95]
	v_mfma_f32_32x32x16_bf16 v[64:79], v[218:221], v[222:225], v[64:79]
	ds_read_b128 v[174:177], v201 offset:57344
	ds_read_b128 v[218:221], v204 offset:57344
	ds_read_b128 v[222:225], v183 offset:2048
	s_waitcnt lgkmcnt(0)
	v_mfma_f32_32x32x16_bf16 v[80:95], v[174:177], v[222:225], v[80:95]
	v_mfma_f32_32x32x16_bf16 v[64:79], v[218:221], v[222:225], v[64:79]
	ds_read_b128 v[174:177], v200 offset:57344
	ds_read_b128 v[218:221], v203 offset:57344
	ds_read_b128 v[222:225], v183 offset:3072
	v_cvt_pk_bf16_f32 v148, v149, v170
	v_cvt_pk_bf16_f32 v149, v150, v171
	v_cvt_pk_bf16_f32 v150, v169, v172
	v_cvt_pk_bf16_f32 v151, v151, v168
	v_cvt_pk_bf16_f32 v152, v147, v152
	v_cvt_pk_bf16_f32 v153, v153, v154
	s_waitcnt lgkmcnt(0)
	v_mfma_f32_32x32x16_bf16 v[80:95], v[174:177], v[222:225], v[80:95]
	v_permlane32_swap_b32_e32 v148, v150
	v_cvt_pk_bf16_f32 v154, v144, v145
	v_cvt_pk_bf16_f32 v155, v146, v155
	v_permlane32_swap_b32_e32 v149, v151
	v_permlane32_swap_b32_e32 v152, v154
	v_mfma_f32_32x32x16_bf16 v[64:79], v[218:221], v[222:225], v[64:79]
	v_mov_b32_e32 v218, v217
	s_nop 1
	v_permlane32_swap_b32_e32 v217, v218
	v_cvt_pk_bf16_f32 v220, v142, v143
	v_cvt_pk_bf16_f32 v221, v140, v141
	v_cvt_pk_bf16_f32 v222, v136, v137
	v_cvt_pk_bf16_f32 v223, v132, v133
	v_cvt_pk_bf16_f32 v224, v130, v131
	v_cvt_pk_bf16_f32 v225, v138, v139
	v_cvt_pk_bf16_f32 v226, v134, v135
	v_cvt_pk_bf16_f32 v227, v128, v129
	v_permlane32_swap_b32_e32 v153, v155
	v_permlane32_swap_b32_e32 v220, v222
	v_permlane32_swap_b32_e32 v221, v223
	v_permlane32_swap_b32_e32 v224, v226
	v_permlane32_swap_b32_e32 v225, v227
	s_add_u32 s34, s32, s38
	s_addc_u32 s35, s33, 0
	s_add_u32 s36, s56, s39
	s_addc_u32 s37, s57, 0
	global_load_dwordx4 v[128:131], v251, s[34:35]
	global_load_dwordx4 v[132:135], v252, s[34:35]
	global_load_dwordx4 v[136:139], v248, s[36:37]
	global_load_dwordx4 v[140:143], v249, s[36:37]
	global_load_dwordx4 v[144:147], v250, s[36:37]
	ds_read_b64_tr_b16 v[228:229], v182 offset:0
	ds_read_b64_tr_b16 v[230:231], v182 offset:0x800
	ds_read_b64_tr_b16 v[232:233], v182 offset:0x1000
	ds_read_b64_tr_b16 v[234:235], v182 offset:0x1800
	ds_read_b64_tr_b16 v[236:237], v182 offset:0x2000
	ds_read_b64_tr_b16 v[238:239], v182 offset:0x2800
	ds_read_b64_tr_b16 v[244:245], v182 offset:0x3000
	ds_read_b64_tr_b16 v[246:247], v182 offset:0x3800
	s_waitcnt lgkmcnt(0)
; #define SBAR() __builtin_amdgcn_sched_barrier(0)
; template <int DK>
; __device__ __forceinline__ void partialSM(f32x16& p0, f32x16& p1, float& m_reg, float& mn, float& alpha) {
;   constexpr float SCALE = Cst<DK>::SCALE, C = SCALE * 1.4426950408889634f;
;   float pmax = p0[0];
; #pragma unroll
;   for (int r = 1; r < 16; ++r) pmax = fmaxf(pmax, p0[r]);
; #pragma unroll
;   for (int r = 0; r < 16; ++r) pmax = fmaxf(pmax, p1[r]);
;   { auto rr = __builtin_amdgcn_permlane32_swap(__float_as_uint(pmax), __float_as_uint(pmax), false, false);
;     pmax = fmaxf(__uint_as_float(rr[0]), __uint_as_float(rr[1])); }
;   if (__builtin_expect(__all(pmax - m_reg <= THR / SCALE), 1)) { mn = m_reg; alpha = 1.f; }
;   else { mn = fmaxf(m_reg, pmax); alpha = __builtin_amdgcn_exp2f((m_reg - mn) * C); m_reg = mn; }
; template <int D0> __device__ __forceinline__ void pv_one(f32x16& od, int vb, bf16x8 pa0, bf16x8 pa1, bf16x8 pa2, bf16x8 pa3) {
;   const s16x4 l0 = tr_read<v_rd_off(D0, 0, 0)>(vb), h0 = tr_read<v_rd_off(D0, 0, 1)>(vb), l1 = tr_read<v_rd_off(D0, 1, 0)>(vb), h1 = tr_read<v_rd_off(D0, 1, 1)>(vb);
;   const s16x4 l2 = tr_read<v_rd_off(D0, 2, 0)>(vb), h2 = tr_read<v_rd_off(D0, 2, 1)>(vb), l3 = tr_read<v_rd_off(D0, 3, 0)>(vb), h3 = tr_read<v_rd_off(D0, 3, 1)>(vb);
;   asm volatile("s_waitcnt lgkmcnt(0)" ::: "memory"); SBAR();
;     ...
;   od = __builtin_amdgcn_mfma_f32_32x32x16_bf16(pa0, PK(l0, h0), od, 0, 0, 0);
;   od = __builtin_amdgcn_mfma_f32_32x32x16_bf16(pa1, PK(l1, h1), od, 0, 0, 0);
;   od = __builtin_amdgcn_mfma_f32_32x32x16_bf16(pa2, PK(l2, h2), od, 0, 0, 0);
;   od = __builtin_amdgcn_mfma_f32_32x32x16_bf16(pa3, PK(l3, h3), od, 0, 0, 0);
;     ...
; }
; __device__ __forceinline__ void pv_d0(f32x16* o, int vb, bf16x8 pa0, bf16x8 pa1, bf16x8 pa2, bf16x8 pa3) {
;   pv_one<0>(o[0], vb, pa0, pa1, pa2, pa3); pv_one<1>(o[1], vb, pa0, pa1, pa2, pa3); pv_one<2>(o[2], vb, pa0, pa1, pa2, pa3); pv_one<3>(o[3], vb, pa0, pa1, pa2, pa3);
; template <int DK, int LDQ, int LDK, int LDV, int LDO, int SDEPTH, int NPARK>
; __device__ __forceinline__ void body(const bf16_t* __restrict__ Qb, const bf16_t* __restrict__ Kh, const bf16_t* __restrict__ Vh, bf16_t* __restrict__ Ob, int seq, char* lds, int tid, int wid) {
;     ...
;     pv_d0(o, vb0, pa0, pa1, pa2, pa3); partialSM<DK>(pB0, pB1, m_reg, mnB, alB);
;     __syncthreads(); SWAIT(); SWRITE(0, SE);
;     RESC(alB); __syncthreads();
	s_nop 0
	v_mfma_f32_32x32x16_bf16 v[0:15], v[148:151], v[228:231], v[0:15]
	ds_read_b64_tr_b16 v[228:229], v182 offset:0x200
	ds_read_b64_tr_b16 v[230:231], v182 offset:0xa00
	v_mfma_f32_32x32x16_bf16 v[0:15], v[152:155], v[232:235], v[0:15]
	ds_read_b64_tr_b16 v[232:233], v182 offset:0x1200
	ds_read_b64_tr_b16 v[234:235], v182 offset:0x1a00
	v_mfma_f32_32x32x16_bf16 v[0:15], v[220:223], v[236:239], v[0:15]
	ds_read_b64_tr_b16 v[236:237], v182 offset:0x2200
	ds_read_b64_tr_b16 v[238:239], v182 offset:0x2a00
	v_mfma_f32_32x32x16_bf16 v[0:15], v[224:227], v[244:247], v[0:15]
	ds_read_b64_tr_b16 v[244:245], v182 offset:0x3200
	ds_read_b64_tr_b16 v[246:247], v182 offset:0x3a00
	s_waitcnt lgkmcnt(0)
	v_mfma_f32_32x32x16_bf16 v[48:63], v[148:151], v[228:231], v[48:63]
	ds_read_b64_tr_b16 v[228:229], v182 offset:0x400
	ds_read_b64_tr_b16 v[230:231], v182 offset:0xc00
	v_mfma_f32_32x32x16_bf16 v[48:63], v[152:155], v[232:235], v[48:63]
	ds_read_b64_tr_b16 v[232:233], v182 offset:0x1400
	ds_read_b64_tr_b16 v[234:235], v182 offset:0x1c00
	v_mfma_f32_32x32x16_bf16 v[48:63], v[220:223], v[236:239], v[48:63]
	ds_read_b64_tr_b16 v[236:237], v182 offset:0x2400
	ds_read_b64_tr_b16 v[238:239], v182 offset:0x2c00
	v_mfma_f32_32x32x16_bf16 v[48:63], v[224:227], v[244:247], v[48:63]
	ds_read_b64_tr_b16 v[244:245], v182 offset:0x3400
	ds_read_b64_tr_b16 v[246:247], v182 offset:0x3c00
	s_waitcnt lgkmcnt(0)
	v_mfma_f32_32x32x16_bf16 v[32:47], v[148:151], v[228:231], v[32:47]
	ds_read_b64_tr_b16 v[228:229], v182 offset:0x600
	ds_read_b64_tr_b16 v[230:231], v182 offset:0xe00
	v_mfma_f32_32x32x16_bf16 v[32:47], v[152:155], v[232:235], v[32:47]
	ds_read_b64_tr_b16 v[232:233], v182 offset:0x1600
	ds_read_b64_tr_b16 v[234:235], v182 offset:0x1e00
	v_mfma_f32_32x32x16_bf16 v[32:47], v[220:223], v[236:239], v[32:47]
	ds_read_b64_tr_b16 v[236:237], v182 offset:0x2600
	ds_read_b64_tr_b16 v[238:239], v182 offset:0x2e00
	v_mfma_f32_32x32x16_bf16 v[32:47], v[224:227], v[244:247], v[32:47]
	ds_read_b64_tr_b16 v[244:245], v182 offset:0x3600
	ds_read_b64_tr_b16 v[246:247], v182 offset:0x3e00
	s_waitcnt lgkmcnt(0)
	v_mfma_f32_32x32x16_bf16 v[16:31], v[148:151], v[228:231], v[16:31]
	v_max_f32_e32 v148, v80, v81
	v_max3_f32 v148, v148, v82, v83
	v_max3_f32 v148, v148, v84, v85
	v_max3_f32 v148, v148, v86, v87
	v_max3_f32 v148, v148, v88, v89
	v_max3_f32 v148, v148, v90, v91
	v_max3_f32 v148, v148, v92, v93
	v_mfma_f32_32x32x16_bf16 v[16:31], v[152:155], v[232:235], v[16:31]
	v_max3_f32 v148, v148, v94, v95
	v_max3_f32 v148, v148, v64, v65
	v_max3_f32 v148, v148, v66, v67
	v_max3_f32 v148, v148, v68, v69
	v_max3_f32 v148, v148, v70, v71
	v_max3_f32 v148, v148, v72, v73
	v_max3_f32 v148, v148, v74, v75
	v_max3_f32 v148, v148, v76, v77
	v_mfma_f32_32x32x16_bf16 v[16:31], v[220:223], v[236:239], v[16:31]
	v_max3_f32 v148, v148, v78, v79
	v_mov_b32_e32 v149, v148
	s_nop 1
	v_permlane32_swap_b32_e32 v148, v149
	v_max_f32_e32 v148, v148, v149
	v_sub_f32_e32 v149, v148, v210
	v_cmp_ge_f32_e32 vcc, s69, v149
	v_max_f32_e32 v148, v210, v148
	v_mfma_f32_32x32x16_bf16 v[16:31], v[224:227], v[244:247], v[16:31]
	v_sub_f32_e32 v149, v210, v148
	v_mul_f32_e32 v149, 0x3dd53b94, v149
	v_exp_f32_e32 v149, v149
	s_cmp_eq_u64 vcc, exec
	s_cselect_b64 s[8:9], -1, 0
	s_barrier
	s_waitcnt vmcnt(0)
	v_cndmask_b32_e64 v219, v149, 1.0, s[8:9]
	v_cmp_gt_f32_e32 vcc, 1.0, v219
	s_waitcnt vmcnt(4)
	ds_write_b128 v184, v[128:131]
	s_waitcnt vmcnt(3)
	ds_write_b128 v185, v[132:135]
	s_waitcnt vmcnt(2)
	ds_write_b128 v189, v[136:139] offset:32768
	s_waitcnt vmcnt(1)
	ds_write_b128 v189, v[140:143] offset:45056
	s_waitcnt vmcnt(0)
	ds_write_b128 v191, v[144:147] offset:32768
	s_cbranch_vccz .LBB0_952
	s_and_saveexec_b64 s[12:13], s[6:7]
	ds_write_b32 v179, v219 offset:128
	s_or_b64 exec, exec, s[12:13]
	s_waitcnt lgkmcnt(0)
	v_add_u32_e32 v140, s59, v192
	ds_read_b128 v[128:131], v140 offset:224
	ds_read_b128 v[132:135], v140 offset:192
	ds_read_b128 v[136:139], v140 offset:160
	ds_read_b128 v[140:143], v140 offset:128
	s_waitcnt lgkmcnt(3)
	v_pk_mul_f32 v[12:13], v[12:13], v[128:129]
	s_waitcnt lgkmcnt(2)
	v_pk_mul_f32 v[8:9], v[8:9], v[132:133]
	s_waitcnt lgkmcnt(1)
	v_pk_mul_f32 v[4:5], v[4:5], v[136:137]
	v_pk_mul_f32 v[14:15], v[14:15], v[130:131]
	v_pk_mul_f32 v[10:11], v[10:11], v[134:135]
	v_pk_mul_f32 v[6:7], v[6:7], v[138:139]
	s_waitcnt lgkmcnt(0)
	v_pk_mul_f32 v[2:3], v[2:3], v[142:143]
	v_pk_mul_f32 v[0:1], v[0:1], v[140:141]
	v_pk_mul_f32 v[60:61], v[60:61], v[128:129]
	v_pk_mul_f32 v[56:57], v[56:57], v[132:133]
	v_pk_mul_f32 v[52:53], v[52:53], v[136:137]
	v_pk_mul_f32 v[62:63], v[62:63], v[130:131]
	v_pk_mul_f32 v[58:59], v[58:59], v[134:135]
	v_pk_mul_f32 v[54:55], v[54:55], v[138:139]
	v_pk_mul_f32 v[50:51], v[50:51], v[142:143]
	v_pk_mul_f32 v[48:49], v[48:49], v[140:141]
	v_pk_mul_f32 v[44:45], v[44:45], v[128:129]
	v_pk_mul_f32 v[40:41], v[40:41], v[132:133]
	v_pk_mul_f32 v[36:37], v[36:37], v[136:137]
	v_pk_mul_f32 v[46:47], v[46:47], v[130:131]
	v_pk_mul_f32 v[42:43], v[42:43], v[134:135]
	v_pk_mul_f32 v[38:39], v[38:39], v[138:139]
	v_pk_mul_f32 v[34:35], v[34:35], v[142:143]
	v_pk_mul_f32 v[32:33], v[32:33], v[140:141]
	v_pk_mul_f32 v[28:29], v[28:29], v[128:129]
	v_pk_mul_f32 v[24:25], v[24:25], v[132:133]
	v_pk_mul_f32 v[20:21], v[20:21], v[136:137]
	v_pk_mul_f32 v[30:31], v[30:31], v[130:131]
	v_pk_mul_f32 v[26:27], v[26:27], v[134:135]
	v_pk_mul_f32 v[22:23], v[22:23], v[138:139]
	v_pk_mul_f32 v[18:19], v[18:19], v[142:143]
	v_pk_mul_f32 v[16:17], v[16:17], v[140:141]
; #define SBAR() __builtin_amdgcn_sched_barrier(0)
; template <int DK>
; __device__ __forceinline__ void partialSM(f32x16& p0, f32x16& p1, float& m_reg, float& mn, float& alpha) {
;     ...
;   float mnC = -mn * C;
; #pragma unroll
;   for (int r = 0; r < 16; ++r) p0[r] = fmaf(p0[r], C, mnC);
; #pragma unroll
;   for (int r = 0; r < 16; ++r) p1[r] = fmaf(p1[r], C, mnC);
; #pragma unroll
;   for (int r = 0; r < 16; ++r) p0[r] = __builtin_amdgcn_exp2f(p0[r]);
; }
; __device__ __forceinline__ void finishSM(f32x16& p0, f32x16& p1, float alpha, float& l_reg, bf16x8& pa0, bf16x8& pa1, bf16x8& pa2, bf16x8& pa3) {
; #pragma unroll
;   for (int r = 0; r < 16; ++r) p1[r] = __builtin_amdgcn_exp2f(p1[r]);
; template <int DK, int LDQ, int LDK, int LDV, int LDO, int SDEPTH, int NPARK>
; __device__ __forceinline__ void body(const bf16_t* __restrict__ Qb, const bf16_t* __restrict__ Kh, const bf16_t* __restrict__ Vh, bf16_t* __restrict__ Ob, int seq, char* lds, int tid, int wid) {
;     ...
;     SBAR(); qkt<DK, NPARK>(pA0, pA1, K_lds, qr, qpark, r32, hi);
;     finishSM(pB0, pB1, alB, l_reg, pa0, pa1, pa2, pa3); SBAR();
.LBB0_952:
	v_cndmask_b32_e64 v210, v148, v210, s[8:9]
	v_mul_f32_e32 v144, 0xbdd53b94, v210
	v_fmamk_f32 v80, v80, 0x3dd53b94, v144
	v_fmamk_f32 v81, v81, 0x3dd53b94, v144
	v_fmamk_f32 v82, v82, 0x3dd53b94, v144
	v_fmamk_f32 v83, v83, 0x3dd53b94, v144
	v_fmamk_f32 v84, v84, 0x3dd53b94, v144
	v_fmamk_f32 v85, v85, 0x3dd53b94, v144
	v_fmamk_f32 v86, v86, 0x3dd53b94, v144
	v_fmamk_f32 v87, v87, 0x3dd53b94, v144
	v_fmamk_f32 v88, v88, 0x3dd53b94, v144
	v_fmamk_f32 v89, v89, 0x3dd53b94, v144
	v_fmamk_f32 v90, v90, 0x3dd53b94, v144
	v_fmamk_f32 v91, v91, 0x3dd53b94, v144
	v_fmamk_f32 v92, v92, 0x3dd53b94, v144
	v_fmamk_f32 v93, v93, 0x3dd53b94, v144
	v_fmamk_f32 v94, v94, 0x3dd53b94, v144
	v_fmamk_f32 v95, v95, 0x3dd53b94, v144
	v_fmamk_f32 v220, v67, 0x3dd53b94, v144
	v_fmamk_f32 v221, v68, 0x3dd53b94, v144
	v_fmamk_f32 v148, v71, 0x3dd53b94, v144
	v_fmamk_f32 v149, v72, 0x3dd53b94, v144
	v_fmamk_f32 v153, v64, 0x3dd53b94, v144
	v_fmamk_f32 v154, v65, 0x3dd53b94, v144
	v_fmamk_f32 v155, v66, 0x3dd53b94, v144
	v_fmamk_f32 v146, v69, 0x3dd53b94, v144
	v_fmamk_f32 v147, v70, 0x3dd53b94, v144
	v_fmamk_f32 v150, v73, 0x3dd53b94, v144
	v_fmamk_f32 v151, v74, 0x3dd53b94, v144
	v_fmamk_f32 v152, v75, 0x3dd53b94, v144
	v_fmamk_f32 v145, v76, 0x3dd53b94, v144
	v_exp_f32_e32 v141, v80
	v_exp_f32_e32 v143, v81
	v_exp_f32_e32 v139, v82
	v_exp_f32_e32 v142, v83
	v_exp_f32_e32 v138, v84
	v_exp_f32_e32 v140, v85
	v_exp_f32_e32 v136, v86
	v_exp_f32_e32 v137, v87
	v_exp_f32_e32 v133, v88
	v_exp_f32_e32 v135, v89
	v_exp_f32_e32 v132, v90
	v_exp_f32_e32 v134, v91
	v_exp_f32_e32 v129, v92
	v_exp_f32_e32 v131, v93
	v_exp_f32_e32 v128, v94
	v_exp_f32_e32 v130, v95
	v_fmamk_f32 v222, v77, 0x3dd53b94, v144
	v_fmamk_f32 v223, v78, 0x3dd53b94, v144
	v_fmac_f32_e32 v144, 0x3dd53b94, v79
	s_waitcnt lgkmcnt(0)
	s_barrier
	ds_read_b128 v[64:67], v196 offset:32768
	ds_read_b128 v[68:71], v196 offset:45056
	ds_read_b128 v[224:227], v199 offset:32768
	ds_read_b128 v[228:231], v199 offset:45056
	v_exp_f32_e32 v146, v146
	v_exp_f32_e32 v147, v147
	s_waitcnt lgkmcnt(3)
	v_mfma_f32_32x32x16_bf16 v[80:95], v[64:67], v[124:127], 0
	v_exp_f32_e32 v145, v145
	v_exp_f32_e32 v144, v144
	s_waitcnt lgkmcnt(2)
	v_mfma_f32_32x32x16_bf16 v[64:79], v[68:71], v[124:127], 0
	s_waitcnt lgkmcnt(0)
	v_mfma_f32_32x32x16_bf16 v[64:79], v[228:231], v[116:119], v[64:79]
	v_mfma_f32_32x32x16_bf16 v[80:95], v[224:227], v[116:119], v[80:95]
	ds_read_b128 v[224:227], v198 offset:32768
	ds_read_b128 v[228:231], v198 offset:45056
	s_waitcnt lgkmcnt(0)
	v_mfma_f32_32x32x16_bf16 v[64:79], v[228:231], v[120:123], v[64:79]
	v_mfma_f32_32x32x16_bf16 v[80:95], v[224:227], v[120:123], v[80:95]
	ds_read_b128 v[224:227], v197 offset:32768
	ds_read_b128 v[228:231], v197 offset:45056
	s_waitcnt lgkmcnt(0)
	v_mfma_f32_32x32x16_bf16 v[64:79], v[228:231], v[112:115], v[64:79]
	v_mfma_f32_32x32x16_bf16 v[80:95], v[224:227], v[112:115], v[80:95]
	ds_read_b128 v[224:227], v195 offset:32768
	ds_read_b128 v[228:231], v195 offset:45056
	s_waitcnt lgkmcnt(0)
	v_mfma_f32_32x32x16_bf16 v[64:79], v[228:231], v[108:111], v[64:79]
	v_mfma_f32_32x32x16_bf16 v[80:95], v[224:227], v[108:111], v[80:95]
	ds_read_b128 v[224:227], v194 offset:32768
	ds_read_b128 v[228:231], v194 offset:45056
	s_waitcnt lgkmcnt(0)
	v_mfma_f32_32x32x16_bf16 v[64:79], v[228:231], v[104:107], v[64:79]
	v_mfma_f32_32x32x16_bf16 v[80:95], v[224:227], v[104:107], v[80:95]
	ds_read_b128 v[224:227], v188 offset:32768
	ds_read_b128 v[228:231], v188 offset:45056
	s_waitcnt lgkmcnt(0)
	v_mfma_f32_32x32x16_bf16 v[64:79], v[228:231], v[100:103], v[64:79]
	v_mfma_f32_32x32x16_bf16 v[80:95], v[224:227], v[100:103], v[80:95]
	ds_read_b128 v[224:227], v187 offset:32768
	ds_read_b128 v[228:231], v187 offset:45056
	s_waitcnt lgkmcnt(0)
	v_mfma_f32_32x32x16_bf16 v[64:79], v[228:231], v[96:99], v[64:79]
	v_mfma_f32_32x32x16_bf16 v[80:95], v[224:227], v[96:99], v[80:95]
	ds_read_b128 v[224:227], v186 offset:32768
	ds_read_b128 v[228:231], v186 offset:45056
	ds_read_b128 v[232:235], v183
	s_waitcnt lgkmcnt(0)
	v_mfma_f32_32x32x16_bf16 v[64:79], v[228:231], v[232:235], v[64:79]
	v_mfma_f32_32x32x16_bf16 v[80:95], v[224:227], v[232:235], v[80:95]
	ds_read_b128 v[224:227], v190 offset:32768
	ds_read_b128 v[228:231], v190 offset:45056
	ds_read_b128 v[232:235], v183 offset:1024
	s_waitcnt lgkmcnt(0)
	v_mfma_f32_32x32x16_bf16 v[64:79], v[228:231], v[232:235], v[64:79]
	v_mfma_f32_32x32x16_bf16 v[80:95], v[224:227], v[232:235], v[80:95]
	ds_read_b128 v[224:227], v201 offset:32768
	ds_read_b128 v[228:231], v201 offset:45056
	ds_read_b128 v[232:235], v183 offset:2048
	s_waitcnt lgkmcnt(0)
	v_mfma_f32_32x32x16_bf16 v[64:79], v[228:231], v[232:235], v[64:79]
	v_mfma_f32_32x32x16_bf16 v[80:95], v[224:227], v[232:235], v[80:95]
	ds_read_b128 v[224:227], v200 offset:32768
	ds_read_b128 v[228:231], v200 offset:45056
	ds_read_b128 v[232:235], v183 offset:3072
	s_waitcnt lgkmcnt(0)
; template <int DK>
; __device__ __forceinline__ void partialSM(f32x16& p0, f32x16& p1, float& m_reg, float& mn, float& alpha) {
; __device__ __forceinline__ void finishSM(f32x16& p0, f32x16& p1, float alpha, float& l_reg, bf16x8& pa0, bf16x8& pa1, bf16x8& pa2, bf16x8& pa3) {
; #pragma unroll
;   for (int r = 0; r < 16; ++r) p1[r] = __builtin_amdgcn_exp2f(p1[r]);
;   float ps = 0;
; #pragma unroll
;   for (int r = 0; r < 16; ++r) ps += p0[r];
; #pragma unroll
;   for (int r = 0; r < 16; ++r) ps += p1[r];
;   { auto rr = __builtin_amdgcn_permlane32_swap(__float_as_uint(ps), __float_as_uint(ps), false, false);
;     ps = __uint_as_float(rr[0]) + __uint_as_float(rr[1]); }
;   l_reg = l_reg * alpha + ps;
;     ...
;   PK4(p0, 0, pa0); PK4(p0, 8, pa1); PK4(p1, 0, pa2); PK4(p1, 8, pa3);
;     ...
; }
; template <int D0> __device__ __forceinline__ void pv_one(f32x16& od, int vb, bf16x8 pa0, bf16x8 pa1, bf16x8 pa2, bf16x8 pa3) {
;   const s16x4 l0 = tr_read<v_rd_off(D0, 0, 0)>(vb), h0 = tr_read<v_rd_off(D0, 0, 1)>(vb), l1 = tr_read<v_rd_off(D0, 1, 0)>(vb), h1 = tr_read<v_rd_off(D0, 1, 1)>(vb);
;   const s16x4 l2 = tr_read<v_rd_off(D0, 2, 0)>(vb), h2 = tr_read<v_rd_off(D0, 2, 1)>(vb), l3 = tr_read<v_rd_off(D0, 3, 0)>(vb), h3 = tr_read<v_rd_off(D0, 3, 1)>(vb);
;   asm volatile("s_waitcnt lgkmcnt(0)" ::: "memory"); SBAR();
;     ...
;   od = __builtin_amdgcn_mfma_f32_32x32x16_bf16(pa0, PK(l0, h0), od, 0, 0, 0);
;   od = __builtin_amdgcn_mfma_f32_32x32x16_bf16(pa1, PK(l1, h1), od, 0, 0, 0);
;   od = __builtin_amdgcn_mfma_f32_32x32x16_bf16(pa2, PK(l2, h2), od, 0, 0, 0);
;   od = __builtin_amdgcn_mfma_f32_32x32x16_bf16(pa3, PK(l3, h3), od, 0, 0, 0);
;     ...
; }
; __device__ __forceinline__ void pv_d0(f32x16* o, int vb, bf16x8 pa0, bf16x8 pa1, bf16x8 pa2, bf16x8 pa3) {
;   pv_one<0>(o[0], vb, pa0, pa1, pa2, pa3); pv_one<1>(o[1], vb, pa0, pa1, pa2, pa3); pv_one<2>(o[2], vb, pa0, pa1, pa2, pa3); pv_one<3>(o[3], vb, pa0, pa1, pa2, pa3);
; template <int DK, int LDQ, int LDK, int LDV, int LDO, int SDEPTH, int NPARK>
; __device__ __forceinline__ void body(const bf16_t* __restrict__ Qb, const bf16_t* __restrict__ Kh, const bf16_t* __restrict__ Vh, bf16_t* __restrict__ Ob, int seq, char* lds, int tid, int wid) {
;     ...
;     if (SDEPTH == 1 || j + 3 < NT) SLOAD(SE, (j + 1 + SDEPTH) * KVBLK); SBAR();
;     pv_d0(o, vb0 + (int)SHM_V, pa0, pa1, pa2, pa3); partialSM<DK>(pA0, pA1, m_reg, mnA, alA);
	v_mfma_f32_32x32x16_bf16 v[64:79], v[228:231], v[232:235], v[64:79]
	v_exp_f32_e32 v229, v148
	v_add_f32_e32 v148, 0, v141
	v_add_f32_e32 v148, v143, v148
	v_add_f32_e32 v148, v139, v148
	v_add_f32_e32 v148, v142, v148
	v_add_f32_e32 v148, v138, v148
	v_add_f32_e32 v148, v140, v148
	v_add_f32_e32 v148, v136, v148
	v_add_f32_e32 v148, v137, v148
	v_add_f32_e32 v148, v133, v148
	v_add_f32_e32 v148, v135, v148
	v_add_f32_e32 v148, v132, v148
	v_add_f32_e32 v148, v134, v148
	v_mfma_f32_32x32x16_bf16 v[80:95], v[224:227], v[232:235], v[80:95]
	v_exp_f32_e32 v224, v153
	v_add_f32_e32 v148, v129, v148
	v_exp_f32_e32 v225, v154
	v_add_f32_e32 v148, v131, v148
	v_exp_f32_e32 v226, v155
	v_add_f32_e32 v148, v128, v148
	v_exp_f32_e32 v227, v220
	v_add_f32_e32 v148, v130, v148
	v_exp_f32_e32 v228, v221
	v_add_f32_e32 v148, v224, v148
	v_add_f32_e32 v148, v225, v148
	v_add_f32_e32 v148, v226, v148
	v_add_f32_e32 v148, v227, v148
	v_exp_f32_e32 v230, v149
	v_add_f32_e32 v148, v228, v148
	v_exp_f32_e32 v231, v150
	v_add_f32_e32 v148, v146, v148
	v_exp_f32_e32 v232, v151
	v_add_f32_e32 v148, v147, v148
	v_exp_f32_e32 v233, v152
	v_add_f32_e32 v148, v229, v148
	v_add_f32_e32 v148, v230, v148
	v_exp_f32_e32 v234, v222
	v_add_f32_e32 v148, v231, v148
	v_exp_f32_e32 v235, v223
	v_add_f32_e32 v148, v232, v148
	v_add_f32_e32 v148, v233, v148
	v_add_f32_e32 v148, v145, v148
	v_add_f32_e32 v148, v234, v148
	v_add_f32_e32 v148, v235, v148
	v_add_f32_e32 v220, v144, v148
	v_mov_b32_e32 v221, v220
	v_cvt_pk_bf16_f32 v148, v141, v143
	v_cvt_pk_bf16_f32 v149, v139, v142
	v_cvt_pk_bf16_f32 v150, v138, v140
	v_cvt_pk_bf16_f32 v151, v136, v137
	s_nop 1
	v_permlane32_swap_b32_e32 v220, v221
	v_permlane32_swap_b32_e32 v148, v150
	v_permlane32_swap_b32_e32 v149, v151
	v_cvt_pk_bf16_f32 v152, v133, v135
	v_cvt_pk_bf16_f32 v153, v132, v134
	v_cvt_pk_bf16_f32 v154, v129, v131
	v_cvt_pk_bf16_f32 v155, v128, v130
	v_cvt_pk_bf16_f32 v222, v224, v225
	v_cvt_pk_bf16_f32 v223, v226, v227
	v_cvt_pk_bf16_f32 v224, v228, v146
	v_cvt_pk_bf16_f32 v225, v147, v229
	v_cvt_pk_bf16_f32 v226, v230, v231
	v_cvt_pk_bf16_f32 v227, v232, v233
	v_cvt_pk_bf16_f32 v228, v145, v234
	v_cvt_pk_bf16_f32 v229, v235, v144
	s_nop 0
	v_permlane32_swap_b32_e32 v152, v154
	v_permlane32_swap_b32_e32 v153, v155
	v_permlane32_swap_b32_e32 v222, v224
	v_permlane32_swap_b32_e32 v223, v225
	v_permlane32_swap_b32_e32 v226, v228
	v_permlane32_swap_b32_e32 v227, v229
	s_add_u32 s34, s32, s63
	s_addc_u32 s35, s33, 0
	s_add_u32 s36, s56, s82
	s_addc_u32 s37, s57, 0
	global_load_dwordx4 v[128:131], v251, s[34:35]
	global_load_dwordx4 v[132:135], v252, s[34:35]
	global_load_dwordx4 v[136:139], v248, s[36:37]
	global_load_dwordx4 v[140:143], v249, s[36:37]
	global_load_dwordx4 v[144:147], v250, s[36:37]
	ds_read_b64_tr_b16 v[168:169], v181 offset:0
	ds_read_b64_tr_b16 v[170:171], v181 offset:0x800
	ds_read_b64_tr_b16 v[172:173], v181 offset:0x1000
	ds_read_b64_tr_b16 v[174:175], v181 offset:0x1800
	ds_read_b64_tr_b16 v[230:231], v181 offset:0x2000
	ds_read_b64_tr_b16 v[232:233], v181 offset:0x2800
	ds_read_b64_tr_b16 v[234:235], v181 offset:0x3000
	ds_read_b64_tr_b16 v[236:237], v181 offset:0x3800
	s_waitcnt lgkmcnt(0)
	s_nop 0
	v_mfma_f32_32x32x16_bf16 v[0:15], v[148:151], v[168:171], v[0:15]
	ds_read_b64_tr_b16 v[168:169], v181 offset:0x200
	ds_read_b64_tr_b16 v[170:171], v181 offset:0xa00
	v_mfma_f32_32x32x16_bf16 v[0:15], v[152:155], v[172:175], v[0:15]
	ds_read_b64_tr_b16 v[172:173], v181 offset:0x1200
	ds_read_b64_tr_b16 v[174:175], v181 offset:0x1a00
	v_mfma_f32_32x32x16_bf16 v[0:15], v[222:225], v[230:233], v[0:15]
	ds_read_b64_tr_b16 v[230:231], v181 offset:0x2200
	ds_read_b64_tr_b16 v[232:233], v181 offset:0x2a00
	v_mfma_f32_32x32x16_bf16 v[0:15], v[226:229], v[234:237], v[0:15]
	ds_read_b64_tr_b16 v[234:235], v181 offset:0x3200
	ds_read_b64_tr_b16 v[236:237], v181 offset:0x3a00
	s_waitcnt lgkmcnt(0)
	v_mfma_f32_32x32x16_bf16 v[48:63], v[148:151], v[168:171], v[48:63]
	ds_read_b64_tr_b16 v[168:169], v181 offset:0x400
	ds_read_b64_tr_b16 v[170:171], v181 offset:0xc00
	v_mfma_f32_32x32x16_bf16 v[48:63], v[152:155], v[172:175], v[48:63]
	ds_read_b64_tr_b16 v[172:173], v181 offset:0x1400
	ds_read_b64_tr_b16 v[174:175], v181 offset:0x1c00
	v_mfma_f32_32x32x16_bf16 v[48:63], v[222:225], v[230:233], v[48:63]
	ds_read_b64_tr_b16 v[230:231], v181 offset:0x2400
	ds_read_b64_tr_b16 v[232:233], v181 offset:0x2c00
	v_mfma_f32_32x32x16_bf16 v[48:63], v[226:229], v[234:237], v[48:63]
	ds_read_b64_tr_b16 v[234:235], v181 offset:0x3400
	ds_read_b64_tr_b16 v[236:237], v181 offset:0x3c00
	s_waitcnt lgkmcnt(0)
	v_mfma_f32_32x32x16_bf16 v[32:47], v[148:151], v[168:171], v[32:47]
	ds_read_b64_tr_b16 v[168:169], v181 offset:0x600
	ds_read_b64_tr_b16 v[170:171], v181 offset:0xe00
	v_mfma_f32_32x32x16_bf16 v[32:47], v[152:155], v[172:175], v[32:47]
	ds_read_b64_tr_b16 v[172:173], v181 offset:0x1600
	ds_read_b64_tr_b16 v[174:175], v181 offset:0x1e00
	v_mfma_f32_32x32x16_bf16 v[32:47], v[222:225], v[230:233], v[32:47]
	ds_read_b64_tr_b16 v[230:231], v181 offset:0x2600
	ds_read_b64_tr_b16 v[232:233], v181 offset:0x2e00
	v_mfma_f32_32x32x16_bf16 v[32:47], v[226:229], v[234:237], v[32:47]
	ds_read_b64_tr_b16 v[234:235], v181 offset:0x3600
	ds_read_b64_tr_b16 v[236:237], v181 offset:0x3e00
	s_waitcnt lgkmcnt(0)
	v_mfma_f32_32x32x16_bf16 v[16:31], v[148:151], v[168:171], v[16:31]
	v_max_f32_e32 v148, v80, v81
	v_max3_f32 v148, v148, v82, v83
	v_max3_f32 v148, v148, v84, v85
	v_max3_f32 v148, v148, v86, v87
	v_max3_f32 v148, v148, v88, v89
	v_max3_f32 v148, v148, v90, v91
	v_max3_f32 v148, v148, v92, v93
	v_mfma_f32_32x32x16_bf16 v[16:31], v[152:155], v[172:175], v[16:31]
	v_max3_f32 v148, v148, v94, v95
	v_max3_f32 v148, v148, v64, v65
	v_max3_f32 v148, v148, v66, v67
	v_max3_f32 v148, v148, v68, v69
	v_max3_f32 v148, v148, v70, v71
	v_max3_f32 v148, v148, v72, v73
	v_max3_f32 v148, v148, v74, v75
	v_max3_f32 v148, v148, v76, v77
	v_mfma_f32_32x32x16_bf16 v[16:31], v[222:225], v[230:233], v[16:31]
	v_max3_f32 v148, v148, v78, v79
	v_mov_b32_e32 v149, v148
	s_nop 1
	v_permlane32_swap_b32_e32 v148, v149
	v_max_f32_e32 v148, v148, v149
	v_sub_f32_e32 v149, v148, v210
	v_cmp_ge_f32_e32 vcc, s69, v149
	v_max_f32_e32 v149, v210, v148
	v_mfma_f32_32x32x16_bf16 v[16:31], v[226:229], v[234:237], v[16:31]
	v_sub_f32_e32 v148, v210, v149
	v_mul_f32_e32 v148, 0x3dd53b94, v148
	v_exp_f32_e32 v148, v148
	s_cmp_eq_u64 vcc, exec
	s_cselect_b64 s[8:9], -1, 0
	s_barrier
; #define SBAR() __builtin_amdgcn_sched_barrier(0)
; #define SWAIT() do { if constexpr (SDEPTH == 2) { if constexpr (DK == 192) asm volatile("s_waitcnt vmcnt(5)" ::: "memory"); else asm volatile("s_waitcnt vmcnt(4)" ::: "memory"); } else asm volatile("s_waitcnt vmcnt(0)" ::: "memory"); } while (0)
; #define RESC(a) do { if (__any((a) < 1.f)) { if (hi == 0) al_l[r32] = (a); asm volatile("s_waitcnt lgkmcnt(0)" ::: "memory"); \
;     _Pragma("unroll") for (int d = 0; d < 4; ++d) _Pragma("unroll") for (int r = 0; r < 16; ++r) o[d][r] *= al_l[crow(r, hi)]; } } while (0)
; template <int DK, int LDQ, int LDK, int LDV, int LDO, int SDEPTH, int NPARK>
; __device__ __forceinline__ void body(const bf16_t* __restrict__ Qb, const bf16_t* __restrict__ Kh, const bf16_t* __restrict__ Vh, bf16_t* __restrict__ Ob, int seq, char* lds, int tid, int wid) {
;     ...
;     __syncthreads(); SWAIT(); SWRITE(0, SE);
;     RESC(alB); __syncthreads();
;     SBAR(); qkt<DK, NPARK>(pA0, pA1, K_lds, qr, qpark, r32, hi);
;     finishSM(pB0, pB1, alB, l_reg, pa0, pa1, pa2, pa3); SBAR();
;     ...
;     __syncthreads(); SWAIT(); SWRITE(1, SO);
;     RESC(alA); __syncthreads();
;   }
	s_waitcnt vmcnt(0)
	v_cndmask_b32_e64 v148, v148, 1.0, s[8:9]
	v_cmp_gt_f32_e32 vcc, 1.0, v148
	s_waitcnt vmcnt(4)
	ds_write_b128 v184, v[128:131] offset:16384
	s_waitcnt vmcnt(3)
	ds_write_b128 v185, v[132:135] offset:16384
	s_waitcnt vmcnt(2)
	ds_write_b128 v189, v[136:139] offset:57344
	s_waitcnt vmcnt(1)
	ds_write_b128 v202, v[140:143] offset:57344
	s_waitcnt vmcnt(0)
	ds_write_b128 v191, v[144:147] offset:57344
	s_cbranch_vccz .LBB0_956
	s_and_saveexec_b64 s[12:13], s[6:7]
	ds_write_b32 v179, v148 offset:128
	s_or_b64 exec, exec, s[12:13]
	s_waitcnt lgkmcnt(0)
	v_add_u32_e32 v140, s59, v192
	ds_read_b128 v[128:131], v140 offset:224
	ds_read_b128 v[132:135], v140 offset:192
	ds_read_b128 v[136:139], v140 offset:160
	ds_read_b128 v[140:143], v140 offset:128
	s_waitcnt lgkmcnt(3)
	v_pk_mul_f32 v[12:13], v[12:13], v[128:129]
	s_waitcnt lgkmcnt(2)
	v_pk_mul_f32 v[8:9], v[8:9], v[132:133]
	s_waitcnt lgkmcnt(1)
	v_pk_mul_f32 v[4:5], v[4:5], v[136:137]
	v_pk_mul_f32 v[14:15], v[14:15], v[130:131]
	v_pk_mul_f32 v[10:11], v[10:11], v[134:135]
	v_pk_mul_f32 v[6:7], v[6:7], v[138:139]
	s_waitcnt lgkmcnt(0)
	v_pk_mul_f32 v[2:3], v[2:3], v[142:143]
	v_pk_mul_f32 v[0:1], v[0:1], v[140:141]
	v_pk_mul_f32 v[60:61], v[60:61], v[128:129]
	v_pk_mul_f32 v[56:57], v[56:57], v[132:133]
	v_pk_mul_f32 v[52:53], v[52:53], v[136:137]
	v_pk_mul_f32 v[62:63], v[62:63], v[130:131]
	v_pk_mul_f32 v[58:59], v[58:59], v[134:135]
	v_pk_mul_f32 v[54:55], v[54:55], v[138:139]
	v_pk_mul_f32 v[50:51], v[50:51], v[142:143]
	v_pk_mul_f32 v[48:49], v[48:49], v[140:141]
	v_pk_mul_f32 v[44:45], v[44:45], v[128:129]
	v_pk_mul_f32 v[40:41], v[40:41], v[132:133]
	v_pk_mul_f32 v[36:37], v[36:37], v[136:137]
	v_pk_mul_f32 v[46:47], v[46:47], v[130:131]
	v_pk_mul_f32 v[42:43], v[42:43], v[134:135]
	v_pk_mul_f32 v[38:39], v[38:39], v[138:139]
	v_pk_mul_f32 v[34:35], v[34:35], v[142:143]
	v_pk_mul_f32 v[32:33], v[32:33], v[140:141]
	v_pk_mul_f32 v[28:29], v[28:29], v[128:129]
	v_pk_mul_f32 v[24:25], v[24:25], v[132:133]
	v_pk_mul_f32 v[20:21], v[20:21], v[136:137]
	v_pk_mul_f32 v[30:31], v[30:31], v[130:131]
	v_pk_mul_f32 v[26:27], v[26:27], v[134:135]
	v_pk_mul_f32 v[22:23], v[22:23], v[138:139]
	v_pk_mul_f32 v[18:19], v[18:19], v[142:143]
	v_pk_mul_f32 v[16:17], v[16:17], v[140:141]
.LBB0_956:
	v_cndmask_b32_e64 v210, v149, v210, s[8:9]
	v_mul_f32_e32 v128, 0xbdd53b94, v210
	v_mov_b32_e32 v129, v128
	v_fmamk_f32 v80, v80, 0x3dd53b94, v128
	v_fmamk_f32 v81, v81, 0x3dd53b94, v128
	v_fmamk_f32 v82, v82, 0x3dd53b94, v128
	v_fmamk_f32 v83, v83, 0x3dd53b94, v128
	v_fmamk_f32 v84, v84, 0x3dd53b94, v128
	v_fmamk_f32 v85, v85, 0x3dd53b94, v128
	v_fmamk_f32 v86, v86, 0x3dd53b94, v128
	v_fmamk_f32 v87, v87, 0x3dd53b94, v128
	v_fmamk_f32 v88, v88, 0x3dd53b94, v128
	v_fmamk_f32 v89, v89, 0x3dd53b94, v128
	v_fmamk_f32 v90, v90, 0x3dd53b94, v128
	v_fmamk_f32 v91, v91, 0x3dd53b94, v128
	v_fmamk_f32 v92, v92, 0x3dd53b94, v128
	v_fmamk_f32 v93, v93, 0x3dd53b94, v128
	v_fmamk_f32 v94, v94, 0x3dd53b94, v128
	v_fmac_f32_e32 v129, 0x3dd53b94, v95
	v_exp_f32_e32 v149, v80
	v_exp_f32_e32 v170, v81
	v_exp_f32_e32 v150, v82
	v_exp_f32_e32 v171, v83
	v_exp_f32_e32 v169, v84
	v_exp_f32_e32 v172, v85
	v_exp_f32_e32 v151, v86
	v_exp_f32_e32 v168, v87
	v_exp_f32_e32 v147, v88
	v_exp_f32_e32 v152, v89
	v_exp_f32_e32 v153, v90
	v_exp_f32_e32 v154, v91
	v_exp_f32_e32 v144, v92
	v_exp_f32_e32 v145, v93
	v_exp_f32_e32 v146, v94
	v_exp_f32_e32 v155, v129
	v_pk_fma_f32 v[142:143], v[64:65], s[78:79], v[128:129] op_sel_hi:[1,0,0]
	v_add_f32_e32 v64, v217, v218
	v_fmac_f32_e32 v64, v215, v180
	v_add_f32_e32 v180, v220, v221
	s_add_i32 s14, s14, 2
	v_pk_fma_f32 v[140:141], v[66:67], s[78:79], v[128:129] op_sel_hi:[1,0,0]
	v_pk_fma_f32 v[136:137], v[68:69], s[78:79], v[128:129] op_sel_hi:[1,0,0]
	v_pk_fma_f32 v[132:133], v[70:71], s[78:79], v[128:129] op_sel_hi:[1,0,0]
	v_pk_fma_f32 v[130:131], v[72:73], s[78:79], v[128:129] op_sel_hi:[1,0,0]
	v_pk_fma_f32 v[138:139], v[74:75], s[78:79], v[128:129] op_sel_hi:[1,0,0]
	v_pk_fma_f32 v[134:135], v[76:77], s[78:79], v[128:129] op_sel_hi:[1,0,0]
	v_pk_fma_f32 v[128:129], v[78:79], s[78:79], v[128:129] op_sel_hi:[1,0,0]
	v_fmac_f32_e32 v180, v64, v219
	s_add_u32 s56, s56, 0x30000
	s_addc_u32 s57, s57, 0
	s_add_u32 s32, s32, 0x20000
	s_addc_u32 s33, s33, 0
	s_cmp_ge_u32 s14, s23
	s_waitcnt lgkmcnt(0)
	s_barrier
	s_cbranch_scc1 .LBB0_958
	v_mov_b32_e32 v215, v148
	s_branch .LBB0_948
